# pipelined gemm<4,8>: staging ds_write/global reload pairs spread one per MFMA group over block 0
# speedup vs baseline: 1.0847x; 1.0051x over previous
; DI f32x4 mfma16(bf16x8 a, bf16x8 b, f32x4 c) { return __builtin_amdgcn_mfma_f32_16x16x32_bf16(a, b, c, 0, 0, 0); }
; #define GLOAD(kt) { GL1(0, kt) GL1(1, kt) GL1(2, kt) GL1(3, kt) }
; #define SSTORE(buf)                              \
;   {                                              \
;     char* as_ = smem + (buf) * BUF;              \
;     char* bs_ = as_ + ASZ;                       \
;     SS1(0) SS1(1) SS1(2) SS1(3)                  \
;   }
; template <int MT, int NT>
; DI void gemm_core(const u16* __restrict__ A, int lda, const u16* __restrict__ B, int ldb, int K,
;                   f32x4 (&acc)[MT][NT], char* smem) {
;     ...
;   for (int kt = 0; kt < nk; ++kt) {
;     __syncthreads();
;     SSTORE((kt + 1) & 1);
;     { const int kn_ = (kt + 2 < nk) ? kt + 2 : nk - 1; GLOAD(kn_); }
;     const char* as = smem + (kt & 1) * BUF;
;     const char* bs = as + ASZ;
; #pragma unroll
;     for (int kk = 0; kk < 2; ++kk) {
;       bf16x8 xf[MT], wf[NT];
; #pragma unroll
;       for (int mi = 0; mi < MT; ++mi)
;         xf[mi] = *(const bf16x8*)(as + (wm * (MT * 16) + mi * 16 + fr) * 128 + (((kk * 4 + fq) ^ fsw) * 16));
; #pragma unroll
;       for (int ni = 0; ni < NT; ++ni)
;         wf[ni] = *(const bf16x8*)(bs + (wn * (NT * 16) + ni * 16 + fr) * 128 + (((kk * 4 + fq) ^ fsw) * 16));
;       __builtin_amdgcn_s_setprio(1);
; #pragma unroll
;       for (int mi = 0; mi < MT; ++mi)
; #pragma unroll
;         for (int ni = 0; ni < NT; ++ni) acc[mi][ni] = mfma16(wf[ni], xf[mi], acc[mi][ni]);
;       __builtin_amdgcn_s_setprio(0);
;     }
.LBB0_131:
	s_add_i32 s4, s1, 0x10000
	s_and_b32 s5, s4, 0x10000
	s_add_i32 s3, s2, 1
	s_min_u32 s2, s2, 13
	s_lshl_b32 s54, s2, 7
	s_and_b32 s1, s1, 0x10000
	v_or_b32_e32 v206, s1, v189
	v_add_u32_e32 v207, v206, v188
	v_add_u32_e32 v206, v206, v187
	v_add3_u32 v170, s5, v0, v173
	s_waitcnt lgkmcnt(10)
	v_mfma_f32_16x16x32_bf16 v[158:161], v[220:223], v[190:193], v[158:161]
	s_waitcnt vmcnt(0)
	ds_write_b128 v170, v[110:113]
	s_waitcnt lgkmcnt(10)
	v_mfma_f32_16x16x32_bf16 v[94:97], v[220:223], v[208:211], v[94:97]
	v_lshl_add_u64 v[110:111], v[162:163], 0, s[54:55]
	global_load_dwordx4 v[110:113], v[110:111], off offset:256
	s_waitcnt lgkmcnt(8)
	v_mfma_f32_16x16x32_bf16 v[62:65], v[220:223], v[212:215], v[62:65]
	ds_write_b128 v170, v[118:121] offset:32768
	s_waitcnt lgkmcnt(3)
	v_mfma_f32_16x16x32_bf16 v[30:33], v[220:223], v[216:219], v[30:33]
	v_lshl_add_u64 v[118:119], v[164:165], 0, s[54:55]
	global_load_dwordx4 v[118:121], v[118:119], off offset:256
	ds_read_b128 v[194:197], v206
	v_mfma_f32_16x16x32_bf16 v[154:157], v[224:227], v[190:193], v[154:157]
	ds_read_b128 v[220:223], v207 offset:32768
	ds_write_b128 v170, v[114:117] offset:8192
	v_mfma_f32_16x16x32_bf16 v[90:93], v[224:227], v[208:211], v[90:93]
	v_lshl_add_u64 v[114:115], v[166:167], 0, s[54:55]
	global_load_dwordx4 v[114:117], v[114:115], off offset:256
	v_mfma_f32_16x16x32_bf16 v[58:61], v[224:227], v[212:215], v[58:61]
	v_mfma_f32_16x16x32_bf16 v[26:29], v[224:227], v[216:219], v[26:29]
	ds_read_b128 v[198:201], v206 offset:2048
	v_mfma_f32_16x16x32_bf16 v[146:149], v[228:231], v[190:193], v[146:149]
	ds_read_b128 v[224:227], v207 offset:34816
	ds_write_b128 v170, v[130:133] offset:40960
	v_mfma_f32_16x16x32_bf16 v[86:89], v[228:231], v[208:211], v[86:89]
	v_lshl_add_u64 v[130:131], v[168:169], 0, s[54:55]
	global_load_dwordx4 v[130:133], v[130:131], off offset:256
	v_mfma_f32_16x16x32_bf16 v[54:57], v[228:231], v[212:215], v[54:57]
	v_mfma_f32_16x16x32_bf16 v[22:25], v[228:231], v[216:219], v[22:25]
	ds_read_b128 v[202:205], v206 offset:4096
	v_mfma_f32_16x16x32_bf16 v[142:145], v[232:235], v[190:193], v[142:145]
	ds_read_b128 v[228:231], v207 offset:36864
	ds_write_b128 v170, v[126:129] offset:16384
	v_mfma_f32_16x16x32_bf16 v[82:85], v[232:235], v[208:211], v[82:85]
	v_lshl_add_u64 v[126:127], v[176:177], 0, s[54:55]
	global_load_dwordx4 v[126:129], v[126:127], off offset:256
	v_mfma_f32_16x16x32_bf16 v[50:53], v[232:235], v[212:215], v[50:53]
	v_mfma_f32_16x16x32_bf16 v[18:21], v[232:235], v[216:219], v[18:21]
	v_mfma_f32_16x16x32_bf16 v[122:125], v[236:239], v[190:193], v[122:125]
	ds_read_b128 v[232:235], v207 offset:38912
	ds_write_b128 v170, v[138:141] offset:49152
	v_mfma_f32_16x16x32_bf16 v[78:81], v[236:239], v[208:211], v[78:81]
	v_lshl_add_u64 v[138:139], v[178:179], 0, s[54:55]
	global_load_dwordx4 v[138:141], v[138:139], off offset:256
	v_mfma_f32_16x16x32_bf16 v[46:49], v[236:239], v[212:215], v[46:49]
	v_mfma_f32_16x16x32_bf16 v[14:17], v[236:239], v[216:219], v[14:17]
	v_mfma_f32_16x16x32_bf16 v[106:109], v[240:243], v[190:193], v[106:109]
	ds_read_b128 v[236:239], v207 offset:40960
	ds_write_b128 v170, v[134:137] offset:24576
	v_mfma_f32_16x16x32_bf16 v[74:77], v[240:243], v[208:211], v[74:77]
	v_lshl_add_u64 v[134:135], v[180:181], 0, s[54:55]
	global_load_dwordx4 v[134:137], v[134:135], off offset:256
	v_mfma_f32_16x16x32_bf16 v[42:45], v[240:243], v[212:215], v[42:45]
	v_mfma_f32_16x16x32_bf16 v[10:13], v[240:243], v[216:219], v[10:13]
	v_mfma_f32_16x16x32_bf16 v[102:105], v[244:247], v[190:193], v[102:105]
	ds_read_b128 v[240:243], v207 offset:43008
	ds_write_b128 v170, v[150:153] offset:57344
	v_mfma_f32_16x16x32_bf16 v[70:73], v[244:247], v[208:211], v[70:73]
	v_lshl_add_u64 v[150:151], v[182:183], 0, s[54:55]
	global_load_dwordx4 v[150:153], v[150:151], off offset:256
	v_mfma_f32_16x16x32_bf16 v[38:41], v[244:247], v[212:215], v[38:41]
	v_mfma_f32_16x16x32_bf16 v[6:9], v[244:247], v[216:219], v[6:9]
	s_waitcnt lgkmcnt(15)
	v_mfma_f32_16x16x32_bf16 v[2:5], v[248:251], v[216:219], v[2:5]
	ds_read_b128 v[244:247], v207 offset:45056
	ds_read_b128 v[216:219], v206 offset:6144
	v_mfma_f32_16x16x32_bf16 v[98:101], v[248:251], v[190:193], v[98:101]
	v_mfma_f32_16x16x32_bf16 v[66:69], v[248:251], v[208:211], v[66:69]
	v_mfma_f32_16x16x32_bf16 v[34:37], v[248:251], v[212:215], v[34:37]
	ds_read_b128 v[248:251], v207 offset:47104
	s_waitcnt lgkmcnt(3)
	s_barrier
;   __device__ __forceinline__ u16* P() const { return (u16*)(ws + O_P); }
; DI f32x4 mfma16(bf16x8 a, bf16x8 b, f32x4 c) { return __builtin_amdgcn_mfma_f32_16x16x32_bf16(a, b, c, 0, 0, 0); }
; #define EPI_LOOP(MT_, NT_)                                                \
;   const int l_ = ltid() & 63, w_ = ltid() >> 6;                           \
;   const int wm_ = w_ >> 1, wn_ = w_ & 1, fr_ = l_ & 15, fq_ = l_ >> 4;    \
;   _Pragma("unroll") for (int mi = 0; mi < MT_; ++mi)                      \
;   _Pragma("unroll") for (int ni = 0; ni < NT_; ++ni)
; template <int MT, int NT>
; DI void gemm_core(const u16* __restrict__ A, int lda, const u16* __restrict__ B, int ldb, int K,
;                   f32x4 (&acc)[MT][NT], char* smem) {
;     ...
;     for (int kk = 0; kk < 2; ++kk) {
;       bf16x8 xf[MT], wf[NT];
; #pragma unroll
;       for (int mi = 0; mi < MT; ++mi)
;         xf[mi] = *(const bf16x8*)(as + (wm * (MT * 16) + mi * 16 + fr) * 128 + (((kk * 4 + fq) ^ fsw) * 16));
; #pragma unroll
;       for (int ni = 0; ni < NT; ++ni)
;         wf[ni] = *(const bf16x8*)(bs + (wn * (NT * 16) + ni * 16 + fr) * 128 + (((kk * 4 + fq) ^ fsw) * 16));
;       __builtin_amdgcn_s_setprio(1);
; #pragma unroll
;       for (int mi = 0; mi < MT; ++mi)
; #pragma unroll
;         for (int ni = 0; ni < NT; ++ni) acc[mi][ni] = mfma16(wf[ni], xf[mi], acc[mi][ni]);
;       __builtin_amdgcn_s_setprio(0);
;     }
;   }
; DI void phase_inproj(const Params& p, int l, char* smem) {
;     ...
;     EPI_LOOP(4, 8) {
;       const int row = r0 + wm_ * 64 + mi * 16 + fr_, col = c0 + wn_ * 128 + ni * 16 + fq_ * 4;
;       if (col < PC) {
;         uint2 o;
;         o.x = pack2(acc[mi][ni][0], acc[mi][ni][1]); o.y = pack2(acc[mi][ni][2], acc[mi][ni][3]);
;         *(uint2*)(p.P() + (size_t)row * PC + col) = o;
	v_or_b32_e32 v206, s5, v186
	v_add_u32_e32 v207, v206, v188
	v_add_u32_e32 v206, v206, v187
	v_mfma_f32_16x16x32_bf16 v[158:161], v[220:223], v[194:197], v[158:161]
	v_mfma_f32_16x16x32_bf16 v[94:97], v[220:223], v[198:201], v[94:97]
	v_mfma_f32_16x16x32_bf16 v[62:65], v[220:223], v[202:205], v[62:65]
	s_waitcnt lgkmcnt(1)
	v_mfma_f32_16x16x32_bf16 v[30:33], v[220:223], v[216:219], v[30:33]
	ds_read_b128 v[190:193], v206
	v_mfma_f32_16x16x32_bf16 v[154:157], v[224:227], v[194:197], v[154:157]
	ds_read_b128 v[220:223], v207 offset:32768
	v_mfma_f32_16x16x32_bf16 v[90:93], v[224:227], v[198:201], v[90:93]
	v_mfma_f32_16x16x32_bf16 v[58:61], v[224:227], v[202:205], v[58:61]
	v_mfma_f32_16x16x32_bf16 v[26:29], v[224:227], v[216:219], v[26:29]
	ds_read_b128 v[208:211], v206 offset:2048
	v_mfma_f32_16x16x32_bf16 v[146:149], v[228:231], v[194:197], v[146:149]
	ds_read_b128 v[224:227], v207 offset:34816
	v_mfma_f32_16x16x32_bf16 v[86:89], v[228:231], v[198:201], v[86:89]
	v_mfma_f32_16x16x32_bf16 v[54:57], v[228:231], v[202:205], v[54:57]
	v_mfma_f32_16x16x32_bf16 v[22:25], v[228:231], v[216:219], v[22:25]
	ds_read_b128 v[212:215], v206 offset:4096
	v_mfma_f32_16x16x32_bf16 v[142:145], v[232:235], v[194:197], v[142:145]
	ds_read_b128 v[228:231], v207 offset:36864
	v_mfma_f32_16x16x32_bf16 v[82:85], v[232:235], v[198:201], v[82:85]
	v_mfma_f32_16x16x32_bf16 v[50:53], v[232:235], v[202:205], v[50:53]
	v_mfma_f32_16x16x32_bf16 v[18:21], v[232:235], v[216:219], v[18:21]
	v_mfma_f32_16x16x32_bf16 v[122:125], v[236:239], v[194:197], v[122:125]
	ds_read_b128 v[232:235], v207 offset:38912
	v_mfma_f32_16x16x32_bf16 v[78:81], v[236:239], v[198:201], v[78:81]
	v_mfma_f32_16x16x32_bf16 v[46:49], v[236:239], v[202:205], v[46:49]
	v_mfma_f32_16x16x32_bf16 v[14:17], v[236:239], v[216:219], v[14:17]
	v_mfma_f32_16x16x32_bf16 v[106:109], v[240:243], v[194:197], v[106:109]
	ds_read_b128 v[236:239], v207 offset:40960
	v_mfma_f32_16x16x32_bf16 v[74:77], v[240:243], v[198:201], v[74:77]
	v_mfma_f32_16x16x32_bf16 v[42:45], v[240:243], v[202:205], v[42:45]
	v_mfma_f32_16x16x32_bf16 v[10:13], v[240:243], v[216:219], v[10:13]
	v_mfma_f32_16x16x32_bf16 v[102:105], v[244:247], v[194:197], v[102:105]
	ds_read_b128 v[240:243], v207 offset:43008
	v_mfma_f32_16x16x32_bf16 v[70:73], v[244:247], v[198:201], v[70:73]
	v_mfma_f32_16x16x32_bf16 v[38:41], v[244:247], v[202:205], v[38:41]
	v_mfma_f32_16x16x32_bf16 v[6:9], v[244:247], v[216:219], v[6:9]
	s_waitcnt lgkmcnt(9)
	v_mfma_f32_16x16x32_bf16 v[2:5], v[248:251], v[216:219], v[2:5]
	ds_read_b128 v[244:247], v207 offset:45056
	ds_read_b128 v[216:219], v206 offset:6144
	v_mfma_f32_16x16x32_bf16 v[98:101], v[248:251], v[194:197], v[98:101]
	v_mfma_f32_16x16x32_bf16 v[66:69], v[248:251], v[198:201], v[66:69]
	v_mfma_f32_16x16x32_bf16 v[34:37], v[248:251], v[202:205], v[34:37]
	ds_read_b128 v[248:251], v207 offset:47104
	s_cmp_lg_u32 s3, 16
	s_mov_b32 s1, s4
	s_mov_b32 s2, s3
	s_cbranch_scc1 .LBB0_131
	s_waitcnt vmcnt(0) lgkmcnt(0)
	v_mov_b32_e32 v170, 0x358637bd
	v_mov_b32_e32 v194, 0x25a08
	v_mbcnt_lo_u32_b32 v195, -1, 0
	v_mbcnt_hi_u32_b32 v196, -1, v195
	v_mov_b32_e32 v197, 0x24000
	v_mov_b32_e32 v198, 0x1fa0
	v_mov_b32_e32 v199, 0x41b17218
	v_mov_b32_e32 v200, 0x7e800
	v_mov_b32_e32 v201, 0xfd0
	v_mov_b32_e32 v202, 0x100
	v_mov_b32_e32 v203, 0x200
	v_mov_b32_e32 v204, 0x7f61b1e6
	v_mov_b32_e32 v205, 0xff800000
	v_mov_b32_e32 v206, 0x3f80
	v_mov_b32_e32 v207, 0x1d400
	s_waitcnt vmcnt(7)
	v_mov_b32_e32 v110, v171
	v_mov_b32_e32 v111, v171
	s_barrier
	s_nop 0
	v_ashrrev_i32_e32 v112, 1, v111
	v_and_b32_e32 v112, 0xffffffc0, v112
	v_and_b32_e32 v0, 15, v110
	s_waitcnt vmcnt(5)
	v_add_u32_e32 v114, s0, v112
	v_lshlrev_b32_e32 v111, 1, v111
	v_lshrrev_b32_e32 v110, 2, v110
	v_and_b32_e32 v111, 0x80, v111
	v_and_b32_e32 v110, 12, v110
	v_or_b32_e32 v115, v114, v0
	v_or3_b32 v110, v110, v111, s19
	v_mad_i64_i32 v[112:113], s[0:1], v115, s91, 0
	v_cmp_gt_i32_e64 s[12:13], s69, v110
	v_lshl_add_u64 v[112:113], s[78:79], 0, v[112:113]
	v_ashrrev_i32_e32 v111, 31, v110
	s_and_saveexec_b64 s[0:1], s[12:13]
	s_cbranch_execz .LBB0_134
	v_lshl_add_u64 v[116:117], v[110:111], 1, v[112:113]
	v_cvt_pk_bf16_f32 v119, v160, v161
	v_cvt_pk_bf16_f32 v118, v158, v159
	global_store_dwordx2 v[116:117], v[118:119], off

; DI f32x4 mfma16(bf16x8 a, bf16x8 b, f32x4 c) { return __builtin_amdgcn_mfma_f32_16x16x32_bf16(a, b, c, 0, 0, 0); }
; #define GLOAD(kt) { GL1(0, kt) GL1(1, kt) GL1(2, kt) GL1(3, kt) }
; #define SSTORE(buf)                              \
;   {                                              \
;     char* as_ = smem + (buf) * BUF;              \
;     char* bs_ = as_ + ASZ;                       \
;     SS1(0) SS1(1) SS1(2) SS1(3)                  \
;   }
; template <int MT, int NT>
; DI void gemm_core(const u16* __restrict__ A, int lda, const u16* __restrict__ B, int ldb, int K,
;                   f32x4 (&acc)[MT][NT], char* smem) {
;     ...
;   for (int kt = 0; kt < nk; ++kt) {
;     __syncthreads();
;     SSTORE((kt + 1) & 1);
;     { const int kn_ = (kt + 2 < nk) ? kt + 2 : nk - 1; GLOAD(kn_); }
;     const char* as = smem + (kt & 1) * BUF;
;     const char* bs = as + ASZ;
; #pragma unroll
;     for (int kk = 0; kk < 2; ++kk) {
;       bf16x8 xf[MT], wf[NT];
; #pragma unroll
;       for (int mi = 0; mi < MT; ++mi)
;         xf[mi] = *(const bf16x8*)(as + (wm * (MT * 16) + mi * 16 + fr) * 128 + (((kk * 4 + fq) ^ fsw) * 16));
; #pragma unroll
;       for (int ni = 0; ni < NT; ++ni)
;         wf[ni] = *(const bf16x8*)(bs + (wn * (NT * 16) + ni * 16 + fr) * 128 + (((kk * 4 + fq) ^ fsw) * 16));
;       __builtin_amdgcn_s_setprio(1);
; #pragma unroll
;       for (int mi = 0; mi < MT; ++mi)
; #pragma unroll
;         for (int ni = 0; ni < NT; ++ni) acc[mi][ni] = mfma16(wf[ni], xf[mi], acc[mi][ni]);
;       __builtin_amdgcn_s_setprio(0);
;     }
.LBB0_235:
	s_add_i32 s6, s1, 0x10000
	s_and_b32 s7, s6, 0x10000
	s_cmp_eq_u32 s1, 0
	s_cselect_b32 s54, 0x100, s63
	s_and_b32 s1, s1, 0x10000
	v_or_b32_e32 v206, s1, v189
	v_add_u32_e32 v207, v206, v188
	v_add_u32_e32 v206, v206, v187
	v_add3_u32 v170, s7, v0, v173
	s_waitcnt lgkmcnt(10)
	v_mfma_f32_16x16x32_bf16 v[158:161], v[220:223], v[190:193], v[158:161]
	s_waitcnt vmcnt(0)
	ds_write_b128 v170, v[110:113]
	s_waitcnt lgkmcnt(10)
	v_mfma_f32_16x16x32_bf16 v[94:97], v[220:223], v[208:211], v[94:97]
	v_lshl_add_u64 v[110:111], v[162:163], 0, s[54:55]
	global_load_dwordx4 v[110:113], v[110:111], off
	s_waitcnt lgkmcnt(8)
	v_mfma_f32_16x16x32_bf16 v[62:65], v[220:223], v[212:215], v[62:65]
	ds_write_b128 v170, v[126:129] offset:32768
	s_waitcnt lgkmcnt(3)
	v_mfma_f32_16x16x32_bf16 v[30:33], v[220:223], v[216:219], v[30:33]
	v_lshl_add_u64 v[126:127], v[164:165], 0, s[54:55]
	global_load_dwordx4 v[126:129], v[126:127], off
	ds_read_b128 v[194:197], v206
	v_mfma_f32_16x16x32_bf16 v[154:157], v[224:227], v[190:193], v[154:157]
	ds_read_b128 v[220:223], v207 offset:32768
	ds_write_b128 v170, v[106:109] offset:8192
	v_mfma_f32_16x16x32_bf16 v[90:93], v[224:227], v[208:211], v[90:93]
	v_lshl_add_u64 v[106:107], v[166:167], 0, s[54:55]
	global_load_dwordx4 v[106:109], v[106:107], off
	v_mfma_f32_16x16x32_bf16 v[58:61], v[224:227], v[212:215], v[58:61]
	v_mfma_f32_16x16x32_bf16 v[26:29], v[224:227], v[216:219], v[26:29]
	ds_read_b128 v[198:201], v206 offset:2048
	v_mfma_f32_16x16x32_bf16 v[150:153], v[228:231], v[190:193], v[150:153]
	ds_read_b128 v[224:227], v207 offset:34816
	ds_write_b128 v170, v[122:125] offset:40960
	v_mfma_f32_16x16x32_bf16 v[86:89], v[228:231], v[208:211], v[86:89]
	v_lshl_add_u64 v[122:123], v[168:169], 0, s[54:55]
	global_load_dwordx4 v[122:125], v[122:123], off
	v_mfma_f32_16x16x32_bf16 v[54:57], v[228:231], v[212:215], v[54:57]
	v_mfma_f32_16x16x32_bf16 v[22:25], v[228:231], v[216:219], v[22:25]
	ds_read_b128 v[202:205], v206 offset:4096
	v_mfma_f32_16x16x32_bf16 v[146:149], v[232:235], v[190:193], v[146:149]
	ds_read_b128 v[228:231], v207 offset:36864
	ds_write_b128 v170, v[102:105] offset:16384
	v_mfma_f32_16x16x32_bf16 v[82:85], v[232:235], v[208:211], v[82:85]
	v_lshl_add_u64 v[102:103], v[176:177], 0, s[54:55]
	global_load_dwordx4 v[102:105], v[102:103], off
	v_mfma_f32_16x16x32_bf16 v[50:53], v[232:235], v[212:215], v[50:53]
	v_mfma_f32_16x16x32_bf16 v[18:21], v[232:235], v[216:219], v[18:21]
	v_mfma_f32_16x16x32_bf16 v[142:145], v[236:239], v[190:193], v[142:145]
	ds_read_b128 v[232:235], v207 offset:38912
	ds_write_b128 v170, v[118:121] offset:49152
	v_mfma_f32_16x16x32_bf16 v[78:81], v[236:239], v[208:211], v[78:81]
	v_lshl_add_u64 v[118:119], v[178:179], 0, s[54:55]
	global_load_dwordx4 v[118:121], v[118:119], off
	v_mfma_f32_16x16x32_bf16 v[46:49], v[236:239], v[212:215], v[46:49]
	v_mfma_f32_16x16x32_bf16 v[14:17], v[236:239], v[216:219], v[14:17]
	v_mfma_f32_16x16x32_bf16 v[138:141], v[240:243], v[190:193], v[138:141]
	ds_read_b128 v[236:239], v207 offset:40960
	ds_write_b128 v170, v[98:101] offset:24576
	v_mfma_f32_16x16x32_bf16 v[74:77], v[240:243], v[208:211], v[74:77]
	v_lshl_add_u64 v[98:99], v[180:181], 0, s[54:55]
	global_load_dwordx4 v[98:101], v[98:99], off
	v_mfma_f32_16x16x32_bf16 v[42:45], v[240:243], v[212:215], v[42:45]
	v_mfma_f32_16x16x32_bf16 v[10:13], v[240:243], v[216:219], v[10:13]
	v_mfma_f32_16x16x32_bf16 v[134:137], v[244:247], v[190:193], v[134:137]
	ds_read_b128 v[240:243], v207 offset:43008
	ds_write_b128 v170, v[114:117] offset:57344
	v_mfma_f32_16x16x32_bf16 v[70:73], v[244:247], v[208:211], v[70:73]
	v_lshl_add_u64 v[114:115], v[182:183], 0, s[54:55]
	global_load_dwordx4 v[114:117], v[114:115], off
	v_mfma_f32_16x16x32_bf16 v[38:41], v[244:247], v[212:215], v[38:41]
	v_mfma_f32_16x16x32_bf16 v[6:9], v[244:247], v[216:219], v[6:9]
	s_waitcnt lgkmcnt(15)
	v_mfma_f32_16x16x32_bf16 v[2:5], v[248:251], v[216:219], v[2:5]
	ds_read_b128 v[244:247], v207 offset:45056
	ds_read_b128 v[216:219], v206 offset:6144
	v_mfma_f32_16x16x32_bf16 v[130:133], v[248:251], v[190:193], v[130:133]
	v_mfma_f32_16x16x32_bf16 v[66:69], v[248:251], v[208:211], v[66:69]
	v_mfma_f32_16x16x32_bf16 v[34:37], v[248:251], v[212:215], v[34:37]
	ds_read_b128 v[248:251], v207 offset:47104
	s_waitcnt lgkmcnt(3)
	s_barrier
; DI f32x4 mfma16(bf16x8 a, bf16x8 b, f32x4 c) { return __builtin_amdgcn_mfma_f32_16x16x32_bf16(a, b, c, 0, 0, 0); }
; #define EPI_LOOP(MT_, NT_)                                                \
;   const int l_ = ltid() & 63, w_ = ltid() >> 6;                           \
;   const int wm_ = w_ >> 1, wn_ = w_ & 1, fr_ = l_ & 15, fq_ = l_ >> 4;    \
;   _Pragma("unroll") for (int mi = 0; mi < MT_; ++mi)                      \
;   _Pragma("unroll") for (int ni = 0; ni < NT_; ++ni)
; template <int MT, int NT>
; DI void gemm_core(const u16* __restrict__ A, int lda, const u16* __restrict__ B, int ldb, int K,
;                   f32x4 (&acc)[MT][NT], char* smem) {
;     ...
;     for (int kk = 0; kk < 2; ++kk) {
;       bf16x8 xf[MT], wf[NT];
; #pragma unroll
;       for (int mi = 0; mi < MT; ++mi)
;         xf[mi] = *(const bf16x8*)(as + (wm * (MT * 16) + mi * 16 + fr) * 128 + (((kk * 4 + fq) ^ fsw) * 16));
; #pragma unroll
;       for (int ni = 0; ni < NT; ++ni)
;         wf[ni] = *(const bf16x8*)(bs + (wn * (NT * 16) + ni * 16 + fr) * 128 + (((kk * 4 + fq) ^ fsw) * 16));
;       __builtin_amdgcn_s_setprio(1);
; #pragma unroll
;       for (int mi = 0; mi < MT; ++mi)
; #pragma unroll
;         for (int ni = 0; ni < NT; ++ni) acc[mi][ni] = mfma16(wf[ni], xf[mi], acc[mi][ni]);
;       __builtin_amdgcn_s_setprio(0);
;     }
;   }
; DI void qx_tile(const Params& p, int l, int rt, int ct, char* smem) {
;     ...
;   EPI_LOOP(4, 8) {
;     const int rl = wm_ * 64 + mi * 16 + fr_, col = c0 + wn_ * 128 + ni * 16 + fq_ * 4;
;     const float rs = rsv[rl];
;     uint2 o;
;     o.x = pack2(acc[mi][ni][0] * rs, acc[mi][ni][1] * rs); o.y = pack2(acc[mi][ni][2] * rs, acc[mi][ni][3] * rs);
;     *(uint2*)(QX + (size_t)(r0 + rl) * LDQ + col) = o;
	v_or_b32_e32 v206, s7, v186
	v_add_u32_e32 v207, v206, v188
	v_add_u32_e32 v206, v206, v187
	v_mfma_f32_16x16x32_bf16 v[158:161], v[220:223], v[194:197], v[158:161]
	v_mfma_f32_16x16x32_bf16 v[94:97], v[220:223], v[198:201], v[94:97]
	v_mfma_f32_16x16x32_bf16 v[62:65], v[220:223], v[202:205], v[62:65]
	s_waitcnt lgkmcnt(1)
	v_mfma_f32_16x16x32_bf16 v[30:33], v[220:223], v[216:219], v[30:33]
	ds_read_b128 v[190:193], v206
	v_mfma_f32_16x16x32_bf16 v[154:157], v[224:227], v[194:197], v[154:157]
	ds_read_b128 v[220:223], v207 offset:32768
	v_mfma_f32_16x16x32_bf16 v[90:93], v[224:227], v[198:201], v[90:93]
	v_mfma_f32_16x16x32_bf16 v[58:61], v[224:227], v[202:205], v[58:61]
	v_mfma_f32_16x16x32_bf16 v[26:29], v[224:227], v[216:219], v[26:29]
	ds_read_b128 v[208:211], v206 offset:2048
	v_mfma_f32_16x16x32_bf16 v[150:153], v[228:231], v[194:197], v[150:153]
	ds_read_b128 v[224:227], v207 offset:34816
	v_mfma_f32_16x16x32_bf16 v[86:89], v[228:231], v[198:201], v[86:89]
	v_mfma_f32_16x16x32_bf16 v[54:57], v[228:231], v[202:205], v[54:57]
	v_mfma_f32_16x16x32_bf16 v[22:25], v[228:231], v[216:219], v[22:25]
	ds_read_b128 v[212:215], v206 offset:4096
	v_mfma_f32_16x16x32_bf16 v[146:149], v[232:235], v[194:197], v[146:149]
	ds_read_b128 v[228:231], v207 offset:36864
	v_mfma_f32_16x16x32_bf16 v[82:85], v[232:235], v[198:201], v[82:85]
	v_mfma_f32_16x16x32_bf16 v[50:53], v[232:235], v[202:205], v[50:53]
	v_mfma_f32_16x16x32_bf16 v[18:21], v[232:235], v[216:219], v[18:21]
	v_mfma_f32_16x16x32_bf16 v[142:145], v[236:239], v[194:197], v[142:145]
	ds_read_b128 v[232:235], v207 offset:38912
	v_mfma_f32_16x16x32_bf16 v[78:81], v[236:239], v[198:201], v[78:81]
	v_mfma_f32_16x16x32_bf16 v[46:49], v[236:239], v[202:205], v[46:49]
	v_mfma_f32_16x16x32_bf16 v[14:17], v[236:239], v[216:219], v[14:17]
	v_mfma_f32_16x16x32_bf16 v[138:141], v[240:243], v[194:197], v[138:141]
	ds_read_b128 v[236:239], v207 offset:40960
	v_mfma_f32_16x16x32_bf16 v[74:77], v[240:243], v[198:201], v[74:77]
	v_mfma_f32_16x16x32_bf16 v[42:45], v[240:243], v[202:205], v[42:45]
	v_mfma_f32_16x16x32_bf16 v[10:13], v[240:243], v[216:219], v[10:13]
	v_mfma_f32_16x16x32_bf16 v[134:137], v[244:247], v[194:197], v[134:137]
	ds_read_b128 v[240:243], v207 offset:43008
	v_mfma_f32_16x16x32_bf16 v[70:73], v[244:247], v[198:201], v[70:73]
	v_mfma_f32_16x16x32_bf16 v[38:41], v[244:247], v[202:205], v[38:41]
	v_mfma_f32_16x16x32_bf16 v[6:9], v[244:247], v[216:219], v[6:9]
	s_waitcnt lgkmcnt(9)
	v_mfma_f32_16x16x32_bf16 v[2:5], v[248:251], v[216:219], v[2:5]
	ds_read_b128 v[244:247], v207 offset:45056
	ds_read_b128 v[216:219], v206 offset:6144
	v_mfma_f32_16x16x32_bf16 v[130:133], v[248:251], v[194:197], v[130:133]
	v_mfma_f32_16x16x32_bf16 v[66:69], v[248:251], v[198:201], v[66:69]
	v_mfma_f32_16x16x32_bf16 v[34:37], v[248:251], v[202:205], v[34:37]
	ds_read_b128 v[248:251], v207 offset:47104
	s_cmp_lg_u32 s6, 0x40000
	s_mov_b32 s1, s6
	s_cbranch_scc1 .LBB0_235
	s_waitcnt vmcnt(0) lgkmcnt(0)
	v_mov_b32_e32 v170, 0x358637bd
	v_mov_b32_e32 v194, 0x25a08
	v_mbcnt_lo_u32_b32 v195, -1, 0
	v_mbcnt_hi_u32_b32 v196, -1, v195
	v_mov_b32_e32 v197, 0x24000
	v_mov_b32_e32 v198, 0x1fa0
	v_mov_b32_e32 v199, 0x41b17218
	v_mov_b32_e32 v200, 0x7e800
	v_mov_b32_e32 v201, 0xfd0
	v_mov_b32_e32 v202, 0x100
	v_mov_b32_e32 v203, 0x200
	v_mov_b32_e32 v204, 0x7f61b1e6
	v_mov_b32_e32 v205, 0xff800000
	v_mov_b32_e32 v206, 0x3f80
	v_mov_b32_e32 v207, 0x1d400
	s_waitcnt vmcnt(1)
	v_mov_b32_e32 v98, v171
	v_mov_b32_e32 v99, v171
	s_barrier
	s_movk_i32 s1, 0xffc0
	v_and_b32_e32 v0, 15, v98
	v_ashrrev_i32_e32 v100, 1, v99
	v_lshlrev_b32_e32 v99, 1, v99
	v_lshrrev_b32_e32 v98, 2, v98
	v_and_or_b32 v0, v100, s1, v0
	v_and_b32_e32 v99, 0x80, v99
	v_and_b32_e32 v98, 12, v98
	v_or3_b32 v98, v98, v99, s0
	v_lshl_add_u32 v99, v0, 2, v197
	ds_read_b32 v106, v99
	v_add_u32_e32 v102, s5, v0
	v_mov_b64_e32 v[100:101], s[86:87]
	s_movk_i32 s6, 0xc80
	v_ashrrev_i32_e32 v99, 31, v98
	v_mad_i64_i32 v[102:103], s[0:1], v102, s6, v[100:101]
	s_waitcnt lgkmcnt(0)
	v_mul_f32_e32 v104, v158, v106
	v_mul_f32_e32 v107, v159, v106
	v_mul_f32_e32 v105, v160, v106
	v_mul_f32_e32 v108, v161, v106
	v_lshlrev_b64 v[98:99], 1, v[98:99]
	v_lshl_add_u64 v[102:103], v[102:103], 0, v[98:99]
	v_cvt_pk_bf16_f32 v105, v105, v108
	v_cvt_pk_bf16_f32 v104, v104, v107
	global_store_dwordx2 v[102:103], v[104:105], off
	v_mul_f32_e32 v104, v154, v106
	v_mul_f32_e32 v107, v155, v106
	v_mul_f32_e32 v105, v156, v106
	v_mul_f32_e32 v108, v157, v106
	v_cvt_pk_bf16_f32 v105, v105, v108
	v_cvt_pk_bf16_f32 v104, v104, v107
	global_store_dwordx2 v[102:103], v[104:105], off offset:32
	v_mul_f32_e32 v104, v150, v106
	v_mul_f32_e32 v107, v151, v106
	v_mul_f32_e32 v105, v152, v106
	v_mul_f32_e32 v108, v153, v106
	v_cvt_pk_bf16_f32 v105, v105, v108
	v_cvt_pk_bf16_f32 v104, v104, v107
	global_store_dwordx2 v[102:103], v[104:105], off offset:64
	v_mul_f32_e32 v104, v146, v106
	v_mul_f32_e32 v107, v147, v106
	v_mul_f32_e32 v105, v148, v106
	v_mul_f32_e32 v108, v149, v106
	v_cvt_pk_bf16_f32 v105, v105, v108
	v_cvt_pk_bf16_f32 v104, v104, v107
	global_store_dwordx2 v[102:103], v[104:105], off offset:96
	v_mul_f32_e32 v104, v142, v106
	v_mul_f32_e32 v107, v143, v106
	v_mul_f32_e32 v105, v144, v106
	v_mul_f32_e32 v108, v145, v106
	v_cvt_pk_bf16_f32 v105, v105, v108
	v_cvt_pk_bf16_f32 v104, v104, v107
	global_store_dwordx2 v[102:103], v[104:105], off offset:128
	v_mul_f32_e32 v104, v138, v106
	v_mul_f32_e32 v107, v139, v106
	v_mul_f32_e32 v105, v140, v106
	v_mul_f32_e32 v108, v141, v106
	v_cvt_pk_bf16_f32 v105, v105, v108
	v_cvt_pk_bf16_f32 v104, v104, v107
	global_store_dwordx2 v[102:103], v[104:105], off offset:160
	v_mul_f32_e32 v104, v134, v106
	v_mul_f32_e32 v107, v135, v106
	v_mul_f32_e32 v105, v136, v106
	v_mul_f32_e32 v108, v137, v106
	v_cvt_pk_bf16_f32 v105, v105, v108
	v_cvt_pk_bf16_f32 v104, v104, v107
	global_store_dwordx2 v[102:103], v[104:105], off offset:192
	v_mul_f32_e32 v104, v130, v106
	v_mul_f32_e32 v107, v131, v106
	v_mul_f32_e32 v105, v132, v106
	v_mul_f32_e32 v106, v133, v106
	v_cvt_pk_bf16_f32 v105, v105, v106
	v_cvt_pk_bf16_f32 v104, v104, v107
	global_store_dwordx2 v[102:103], v[104:105], off offset:224
	v_or_b32_e32 v102, 16, v0
	v_lshl_add_u32 v104, v102, 2, v197
	ds_read_b32 v104, v104
	v_add_u32_e32 v102, s5, v102
	v_mad_i64_i32 v[102:103], s[0:1], v102, s6, v[100:101]
	s_add_i32 s4, s4, 1
	s_waitcnt lgkmcnt(0)
; #define EPI_LOOP(MT_, NT_)                                                \
;   const int l_ = ltid() & 63, w_ = ltid() >> 6;                           \
;   const int wm_ = w_ >> 1, wn_ = w_ & 1, fr_ = l_ & 15, fq_ = l_ >> 4;    \
;   _Pragma("unroll") for (int mi = 0; mi < MT_; ++mi)                      \
;   _Pragma("unroll") for (int ni = 0; ni < NT_; ++ni)
; DI void qx_tile(const Params& p, int l, int rt, int ct, char* smem) {
;     ...
;   EPI_LOOP(4, 8) {
;     const int rl = wm_ * 64 + mi * 16 + fr_, col = c0 + wn_ * 128 + ni * 16 + fq_ * 4;
;     const float rs = rsv[rl];
;     uint2 o;
;     o.x = pack2(acc[mi][ni][0] * rs, acc[mi][ni][1] * rs); o.y = pack2(acc[mi][ni][2] * rs, acc[mi][ni][3] * rs);
;     *(uint2*)(QX + (size_t)(r0 + rl) * LDQ + col) = o;
;   }
;   __syncthreads();
	v_mul_f32_e32 v105, v94, v104
	v_mul_f32_e32 v106, v95, v104
	v_mul_f32_e32 v96, v96, v104
	v_mul_f32_e32 v97, v97, v104
	v_lshl_add_u64 v[94:95], v[102:103], 0, v[98:99]
	v_cvt_pk_bf16_f32 v97, v96, v97
	v_cvt_pk_bf16_f32 v96, v105, v106
	global_store_dwordx2 v[94:95], v[96:97], off
	v_mul_f32_e32 v90, v90, v104
	v_mul_f32_e32 v96, v91, v104
	v_mul_f32_e32 v91, v92, v104
	v_mul_f32_e32 v92, v93, v104
	v_cvt_pk_bf16_f32 v91, v91, v92
	v_cvt_pk_bf16_f32 v90, v90, v96
	global_store_dwordx2 v[94:95], v[90:91], off offset:32
	v_mul_f32_e32 v86, v86, v104
	v_mul_f32_e32 v90, v87, v104
	v_mul_f32_e32 v87, v88, v104
	v_mul_f32_e32 v88, v89, v104
	v_cvt_pk_bf16_f32 v87, v87, v88
	v_cvt_pk_bf16_f32 v86, v86, v90
	global_store_dwordx2 v[94:95], v[86:87], off offset:64
	v_mul_f32_e32 v82, v82, v104
	v_mul_f32_e32 v86, v83, v104
	v_mul_f32_e32 v83, v84, v104
	v_mul_f32_e32 v84, v85, v104
	v_cvt_pk_bf16_f32 v83, v83, v84
	v_cvt_pk_bf16_f32 v82, v82, v86
	global_store_dwordx2 v[94:95], v[82:83], off offset:96
	v_mul_f32_e32 v78, v78, v104
	v_mul_f32_e32 v82, v79, v104
	v_mul_f32_e32 v79, v80, v104
	v_mul_f32_e32 v80, v81, v104
	v_cvt_pk_bf16_f32 v79, v79, v80
	v_cvt_pk_bf16_f32 v78, v78, v82
	global_store_dwordx2 v[94:95], v[78:79], off offset:128
	v_mul_f32_e32 v74, v74, v104
	v_mul_f32_e32 v78, v75, v104
	v_mul_f32_e32 v75, v76, v104
	v_mul_f32_e32 v76, v77, v104
	v_cvt_pk_bf16_f32 v75, v75, v76
	v_cvt_pk_bf16_f32 v74, v74, v78
	global_store_dwordx2 v[94:95], v[74:75], off offset:160
	v_mul_f32_e32 v70, v70, v104
	v_mul_f32_e32 v74, v71, v104
	v_mul_f32_e32 v71, v72, v104
	v_mul_f32_e32 v72, v73, v104
	v_cvt_pk_bf16_f32 v71, v71, v72
	v_cvt_pk_bf16_f32 v70, v70, v74
	global_store_dwordx2 v[94:95], v[70:71], off offset:192
	v_mul_f32_e32 v66, v66, v104
	v_mul_f32_e32 v70, v67, v104
	v_mul_f32_e32 v67, v68, v104
	v_mul_f32_e32 v68, v69, v104
	v_cvt_pk_bf16_f32 v67, v67, v68
	v_cvt_pk_bf16_f32 v66, v66, v70
	global_store_dwordx2 v[94:95], v[66:67], off offset:224
	v_or_b32_e32 v66, 32, v0
	v_lshl_add_u32 v68, v66, 2, v197
	ds_read_b32 v68, v68
	v_add_u32_e32 v66, s5, v66
	v_mad_i64_i32 v[66:67], s[0:1], v66, s6, v[100:101]
	v_or_b32_e32 v0, 48, v0
	s_waitcnt lgkmcnt(0)
	v_mul_f32_e32 v69, v62, v68
	v_mul_f32_e32 v70, v63, v68
	v_mul_f32_e32 v64, v64, v68
	v_mul_f32_e32 v65, v65, v68
	v_lshl_add_u64 v[62:63], v[66:67], 0, v[98:99]
	v_cvt_pk_bf16_f32 v65, v64, v65
	v_cvt_pk_bf16_f32 v64, v69, v70
	global_store_dwordx2 v[62:63], v[64:65], off
	v_mul_f32_e32 v58, v58, v68
	v_mul_f32_e32 v64, v59, v68
	v_mul_f32_e32 v59, v60, v68
	v_mul_f32_e32 v60, v61, v68
	v_cvt_pk_bf16_f32 v59, v59, v60
	v_cvt_pk_bf16_f32 v58, v58, v64
	global_store_dwordx2 v[62:63], v[58:59], off offset:32
	v_mul_f32_e32 v54, v54, v68
	v_mul_f32_e32 v58, v55, v68
	v_mul_f32_e32 v55, v56, v68
	v_mul_f32_e32 v56, v57, v68
	v_cvt_pk_bf16_f32 v55, v55, v56
	v_cvt_pk_bf16_f32 v54, v54, v58
	global_store_dwordx2 v[62:63], v[54:55], off offset:64
	v_mul_f32_e32 v50, v50, v68
	v_mul_f32_e32 v54, v51, v68
	v_mul_f32_e32 v51, v52, v68
	v_mul_f32_e32 v52, v53, v68
	v_cvt_pk_bf16_f32 v51, v51, v52
	v_cvt_pk_bf16_f32 v50, v50, v54
	global_store_dwordx2 v[62:63], v[50:51], off offset:96
	v_mul_f32_e32 v46, v46, v68
	v_mul_f32_e32 v50, v47, v68
	v_mul_f32_e32 v47, v48, v68
	v_mul_f32_e32 v48, v49, v68
	v_cvt_pk_bf16_f32 v47, v47, v48
	v_cvt_pk_bf16_f32 v46, v46, v50
	global_store_dwordx2 v[62:63], v[46:47], off offset:128
	v_mul_f32_e32 v42, v42, v68
	v_mul_f32_e32 v46, v43, v68
	v_mul_f32_e32 v43, v44, v68
	v_mul_f32_e32 v44, v45, v68
	v_cvt_pk_bf16_f32 v43, v43, v44
	v_cvt_pk_bf16_f32 v42, v42, v46
	global_store_dwordx2 v[62:63], v[42:43], off offset:160
	v_mul_f32_e32 v38, v38, v68
	v_mul_f32_e32 v42, v39, v68
	v_mul_f32_e32 v39, v40, v68
	v_mul_f32_e32 v40, v41, v68
	v_cvt_pk_bf16_f32 v39, v39, v40
	v_cvt_pk_bf16_f32 v38, v38, v42
	global_store_dwordx2 v[62:63], v[38:39], off offset:192
	v_mul_f32_e32 v34, v34, v68
	v_mul_f32_e32 v38, v35, v68
	v_mul_f32_e32 v35, v36, v68
	v_mul_f32_e32 v36, v37, v68
	v_cvt_pk_bf16_f32 v35, v35, v36
	v_cvt_pk_bf16_f32 v34, v34, v38
	v_lshl_add_u32 v36, v0, 2, v197
	v_add_u32_e32 v0, s5, v0
	global_store_dwordx2 v[62:63], v[34:35], off offset:224
	v_mad_i64_i32 v[34:35], s[0:1], v0, s6, v[100:101]
	ds_read_b32 v0, v36
	s_mov_b64 s[0:1], 0
	s_waitcnt lgkmcnt(0)
	v_mul_f32_e32 v36, v30, v0
	v_mul_f32_e32 v37, v31, v0
	v_mul_f32_e32 v32, v32, v0
	v_mul_f32_e32 v33, v33, v0
	v_lshl_add_u64 v[30:31], v[34:35], 0, v[98:99]
	v_cvt_pk_bf16_f32 v33, v32, v33
	v_cvt_pk_bf16_f32 v32, v36, v37
	global_store_dwordx2 v[30:31], v[32:33], off
	v_mul_f32_e32 v26, v26, v0
	v_mul_f32_e32 v32, v27, v0
	v_mul_f32_e32 v27, v28, v0
	v_mul_f32_e32 v28, v29, v0
	v_cvt_pk_bf16_f32 v27, v27, v28
	v_cvt_pk_bf16_f32 v26, v26, v32
	global_store_dwordx2 v[30:31], v[26:27], off offset:32
	v_mul_f32_e32 v22, v22, v0
	v_mul_f32_e32 v26, v23, v0
	v_mul_f32_e32 v23, v24, v0
	v_mul_f32_e32 v24, v25, v0
	v_cvt_pk_bf16_f32 v23, v23, v24
	v_cvt_pk_bf16_f32 v22, v22, v26
	global_store_dwordx2 v[30:31], v[22:23], off offset:64
	v_mul_f32_e32 v18, v18, v0
	v_mul_f32_e32 v22, v19, v0
	v_mul_f32_e32 v19, v20, v0
	v_mul_f32_e32 v20, v21, v0
	v_cvt_pk_bf16_f32 v19, v19, v20
	v_cvt_pk_bf16_f32 v18, v18, v22
	global_store_dwordx2 v[30:31], v[18:19], off offset:96
	v_mul_f32_e32 v14, v14, v0
	v_mul_f32_e32 v18, v15, v0
	v_mul_f32_e32 v15, v16, v0
	v_mul_f32_e32 v16, v17, v0
	v_cvt_pk_bf16_f32 v15, v15, v16
	v_cvt_pk_bf16_f32 v14, v14, v18
	global_store_dwordx2 v[30:31], v[14:15], off offset:128
	v_mul_f32_e32 v10, v10, v0
	v_mul_f32_e32 v14, v11, v0
	v_mul_f32_e32 v11, v12, v0
	v_mul_f32_e32 v12, v13, v0
	v_cvt_pk_bf16_f32 v11, v11, v12
	v_cvt_pk_bf16_f32 v10, v10, v14
	global_store_dwordx2 v[30:31], v[10:11], off offset:160
	v_mul_f32_e32 v6, v6, v0
	v_mul_f32_e32 v10, v7, v0
	v_mul_f32_e32 v7, v8, v0
	v_mul_f32_e32 v8, v9, v0
	v_cvt_pk_bf16_f32 v7, v7, v8
	v_cvt_pk_bf16_f32 v6, v6, v10
	global_store_dwordx2 v[30:31], v[6:7], off offset:192
	v_mul_f32_e32 v2, v2, v0
	v_mul_f32_e32 v6, v3, v0
	v_mul_f32_e32 v3, v4, v0
	v_mul_f32_e32 v0, v5, v0
	v_cvt_pk_bf16_f32 v3, v3, v0
	v_cvt_pk_bf16_f32 v2, v2, v6
	global_store_dwordx2 v[30:31], v[2:3], off offset:224
	s_barrier
	s_branch .LBB0_228

; DI f32x4 mfma16(bf16x8 a, bf16x8 b, f32x4 c) { return __builtin_amdgcn_mfma_f32_16x16x32_bf16(a, b, c, 0, 0, 0); }
; #define GLOAD(kt) { GL1(0, kt) GL1(1, kt) GL1(2, kt) GL1(3, kt) }
; #define SSTORE(buf)                              \
;   {                                              \
;     char* as_ = smem + (buf) * BUF;              \
;     char* bs_ = as_ + ASZ;                       \
;     SS1(0) SS1(1) SS1(2) SS1(3)                  \
;   }
; template <int MT, int NT>
; DI void gemm_core(const u16* __restrict__ A, int lda, const u16* __restrict__ B, int ldb, int K,
;                   f32x4 (&acc)[MT][NT], char* smem) {
;     ...
;   for (int kt = 0; kt < nk; ++kt) {
;     __syncthreads();
;     SSTORE((kt + 1) & 1);
;     { const int kn_ = (kt + 2 < nk) ? kt + 2 : nk - 1; GLOAD(kn_); }
;     const char* as = smem + (kt & 1) * BUF;
;     const char* bs = as + ASZ;
; #pragma unroll
;     for (int kk = 0; kk < 2; ++kk) {
;       bf16x8 xf[MT], wf[NT];
; #pragma unroll
;       for (int mi = 0; mi < MT; ++mi)
;         xf[mi] = *(const bf16x8*)(as + (wm * (MT * 16) + mi * 16 + fr) * 128 + (((kk * 4 + fq) ^ fsw) * 16));
; #pragma unroll
;       for (int ni = 0; ni < NT; ++ni)
;         wf[ni] = *(const bf16x8*)(bs + (wn * (NT * 16) + ni * 16 + fr) * 128 + (((kk * 4 + fq) ^ fsw) * 16));
;       __builtin_amdgcn_s_setprio(1);
; #pragma unroll
;       for (int mi = 0; mi < MT; ++mi)
; #pragma unroll
;         for (int ni = 0; ni < NT; ++ni) acc[mi][ni] = mfma16(wf[ni], xf[mi], acc[mi][ni]);
;       __builtin_amdgcn_s_setprio(0);
;     }
.LBB0_713:
	s_add_i32 s8, s5, 0x10000
	s_and_b32 s9, s8, 0x10000
	s_add_i32 s7, s6, 1
	s_min_u32 s6, s6, 13
	s_lshl_b32 s54, s6, 7
	s_and_b32 s5, s5, 0x10000
	v_or_b32_e32 v206, s5, v189
	v_add_u32_e32 v207, v206, v188
	v_add_u32_e32 v206, v206, v187
	v_add3_u32 v170, s9, v0, v173
	s_waitcnt lgkmcnt(10)
	v_mfma_f32_16x16x32_bf16 v[158:161], v[220:223], v[190:193], v[158:161]
	s_waitcnt vmcnt(0)
	ds_write_b128 v170, v[114:117]
	s_waitcnt lgkmcnt(10)
	v_mfma_f32_16x16x32_bf16 v[94:97], v[220:223], v[208:211], v[94:97]
	v_lshl_add_u64 v[114:115], v[162:163], 0, s[54:55]
	global_load_dwordx4 v[114:117], v[114:115], off offset:256
	s_waitcnt lgkmcnt(8)
	v_mfma_f32_16x16x32_bf16 v[62:65], v[220:223], v[212:215], v[62:65]
	ds_write_b128 v170, v[122:125] offset:32768
	s_waitcnt lgkmcnt(3)
	v_mfma_f32_16x16x32_bf16 v[30:33], v[220:223], v[216:219], v[30:33]
	v_lshl_add_u64 v[122:123], v[164:165], 0, s[54:55]
	global_load_dwordx4 v[122:125], v[122:123], off offset:256
	ds_read_b128 v[194:197], v206
	v_mfma_f32_16x16x32_bf16 v[150:153], v[224:227], v[190:193], v[150:153]
	ds_read_b128 v[220:223], v207 offset:32768
	ds_write_b128 v170, v[118:121] offset:8192
	v_mfma_f32_16x16x32_bf16 v[90:93], v[224:227], v[208:211], v[90:93]
	v_lshl_add_u64 v[118:119], v[166:167], 0, s[54:55]
	global_load_dwordx4 v[118:121], v[118:119], off offset:256
	v_mfma_f32_16x16x32_bf16 v[58:61], v[224:227], v[212:215], v[58:61]
	v_mfma_f32_16x16x32_bf16 v[26:29], v[224:227], v[216:219], v[26:29]
	ds_read_b128 v[198:201], v206 offset:2048
	v_mfma_f32_16x16x32_bf16 v[146:149], v[228:231], v[190:193], v[146:149]
	ds_read_b128 v[224:227], v207 offset:34816
	ds_write_b128 v170, v[134:137] offset:40960
	v_mfma_f32_16x16x32_bf16 v[86:89], v[228:231], v[208:211], v[86:89]
	v_lshl_add_u64 v[134:135], v[168:169], 0, s[54:55]
	global_load_dwordx4 v[134:137], v[134:135], off offset:256
	v_mfma_f32_16x16x32_bf16 v[54:57], v[228:231], v[212:215], v[54:57]
	v_mfma_f32_16x16x32_bf16 v[22:25], v[228:231], v[216:219], v[22:25]
	ds_read_b128 v[202:205], v206 offset:4096
	v_mfma_f32_16x16x32_bf16 v[126:129], v[232:235], v[190:193], v[126:129]
	ds_read_b128 v[228:231], v207 offset:36864
	ds_write_b128 v170, v[130:133] offset:16384
	v_mfma_f32_16x16x32_bf16 v[82:85], v[232:235], v[208:211], v[82:85]
	v_lshl_add_u64 v[130:131], v[176:177], 0, s[54:55]
	global_load_dwordx4 v[130:133], v[130:131], off offset:256
	v_mfma_f32_16x16x32_bf16 v[50:53], v[232:235], v[212:215], v[50:53]
	v_mfma_f32_16x16x32_bf16 v[18:21], v[232:235], v[216:219], v[18:21]
	v_mfma_f32_16x16x32_bf16 v[110:113], v[236:239], v[190:193], v[110:113]
	ds_read_b128 v[232:235], v207 offset:38912
	ds_write_b128 v170, v[142:145] offset:49152
	v_mfma_f32_16x16x32_bf16 v[78:81], v[236:239], v[208:211], v[78:81]
	v_lshl_add_u64 v[142:143], v[178:179], 0, s[54:55]
	global_load_dwordx4 v[142:145], v[142:143], off offset:256
	v_mfma_f32_16x16x32_bf16 v[46:49], v[236:239], v[212:215], v[46:49]
	v_mfma_f32_16x16x32_bf16 v[14:17], v[236:239], v[216:219], v[14:17]
	v_mfma_f32_16x16x32_bf16 v[106:109], v[240:243], v[190:193], v[106:109]
	ds_read_b128 v[236:239], v207 offset:40960
	ds_write_b128 v170, v[138:141] offset:24576
	v_mfma_f32_16x16x32_bf16 v[74:77], v[240:243], v[208:211], v[74:77]
	v_lshl_add_u64 v[138:139], v[180:181], 0, s[54:55]
	global_load_dwordx4 v[138:141], v[138:139], off offset:256
	v_mfma_f32_16x16x32_bf16 v[42:45], v[240:243], v[212:215], v[42:45]
	v_mfma_f32_16x16x32_bf16 v[10:13], v[240:243], v[216:219], v[10:13]
	v_mfma_f32_16x16x32_bf16 v[102:105], v[244:247], v[190:193], v[102:105]
	ds_read_b128 v[240:243], v207 offset:43008
	ds_write_b128 v170, v[154:157] offset:57344
	v_mfma_f32_16x16x32_bf16 v[70:73], v[244:247], v[208:211], v[70:73]
	v_lshl_add_u64 v[154:155], v[182:183], 0, s[54:55]
	global_load_dwordx4 v[154:157], v[154:155], off offset:256
	v_mfma_f32_16x16x32_bf16 v[38:41], v[244:247], v[212:215], v[38:41]
	v_mfma_f32_16x16x32_bf16 v[6:9], v[244:247], v[216:219], v[6:9]
	s_waitcnt lgkmcnt(15)
	v_mfma_f32_16x16x32_bf16 v[2:5], v[248:251], v[216:219], v[2:5]
	ds_read_b128 v[244:247], v207 offset:45056
	ds_read_b128 v[216:219], v206 offset:6144
	v_mfma_f32_16x16x32_bf16 v[98:101], v[248:251], v[190:193], v[98:101]
	v_mfma_f32_16x16x32_bf16 v[66:69], v[248:251], v[208:211], v[66:69]
	v_mfma_f32_16x16x32_bf16 v[34:37], v[248:251], v[212:215], v[34:37]
	ds_read_b128 v[248:251], v207 offset:47104
	s_waitcnt lgkmcnt(3)
	s_barrier
;   __device__ __forceinline__ u16* XB() const { return (u16*)(ws + O_XB); }
; DI float bflo(u32 v) { return __uint_as_float(v << 16); }
; DI float bfhi(u32 v) { return __uint_as_float(v & 0xffff0000u); }
; DI f32x4 mfma16(bf16x8 a, bf16x8 b, f32x4 c) { return __builtin_amdgcn_mfma_f32_16x16x32_bf16(a, b, c, 0, 0, 0); }
; #define EPI_LOOP(MT_, NT_)                                                \
;   const int l_ = ltid() & 63, w_ = ltid() >> 6;                           \
;   const int wm_ = w_ >> 1, wn_ = w_ & 1, fr_ = l_ & 15, fq_ = l_ >> 4;    \
;   _Pragma("unroll") for (int mi = 0; mi < MT_; ++mi)                      \
;   _Pragma("unroll") for (int ni = 0; ni < NT_; ++ni)
; template <int MT, int NT>
; DI void gemm_core(const u16* __restrict__ A, int lda, const u16* __restrict__ B, int ldb, int K,
;                   f32x4 (&acc)[MT][NT], char* smem) {
;     ...
;     for (int kk = 0; kk < 2; ++kk) {
;       bf16x8 xf[MT], wf[NT];
; #pragma unroll
;       for (int mi = 0; mi < MT; ++mi)
;         xf[mi] = *(const bf16x8*)(as + (wm * (MT * 16) + mi * 16 + fr) * 128 + (((kk * 4 + fq) ^ fsw) * 16));
; #pragma unroll
;       for (int ni = 0; ni < NT; ++ni)
;         wf[ni] = *(const bf16x8*)(bs + (wn * (NT * 16) + ni * 16 + fr) * 128 + (((kk * 4 + fq) ^ fsw) * 16));
;       __builtin_amdgcn_s_setprio(1);
; #pragma unroll
;       for (int mi = 0; mi < MT; ++mi)
; #pragma unroll
;         for (int ni = 0; ni < NT; ++ni) acc[mi][ni] = mfma16(wf[ni], xf[mi], acc[mi][ni]);
;       __builtin_amdgcn_s_setprio(0);
;     }
;   }
; DI void phase_resgemm(const Params& p, const u16* A, int lda, const u16* W, int ldw, int K, char* smem) {
;     ...
;     EPI_LOOP(4, 8) {
;       const int row = r0 + wm_ * 64 + mi * 16 + fr_, col = c0 + wn_ * 128 + ni * 16 + fq_ * 4;
;       const uint2 xb = *(const uint2*)(p.XB() + (size_t)row * LDX + col);
;       float4 o;
;       o.x = DN_ALPHA * bflo(xb.x) + acc[mi][ni][0]; o.y = DN_ALPHA * bfhi(xb.x) + acc[mi][ni][1];
;       o.z = DN_ALPHA * bflo(xb.y) + acc[mi][ni][2]; o.w = DN_ALPHA * bfhi(xb.y) + acc[mi][ni][3];
;       *(float4*)(p.out + (size_t)row * 1024 + col) = o;
	v_or_b32_e32 v206, s9, v186
	v_add_u32_e32 v207, v206, v188
	v_add_u32_e32 v206, v206, v187
	v_mfma_f32_16x16x32_bf16 v[158:161], v[220:223], v[194:197], v[158:161]
	v_mfma_f32_16x16x32_bf16 v[94:97], v[220:223], v[198:201], v[94:97]
	v_mfma_f32_16x16x32_bf16 v[62:65], v[220:223], v[202:205], v[62:65]
	s_waitcnt lgkmcnt(1)
	v_mfma_f32_16x16x32_bf16 v[30:33], v[220:223], v[216:219], v[30:33]
	ds_read_b128 v[190:193], v206
	v_mfma_f32_16x16x32_bf16 v[150:153], v[224:227], v[194:197], v[150:153]
	ds_read_b128 v[220:223], v207 offset:32768
	v_mfma_f32_16x16x32_bf16 v[90:93], v[224:227], v[198:201], v[90:93]
	v_mfma_f32_16x16x32_bf16 v[58:61], v[224:227], v[202:205], v[58:61]
	v_mfma_f32_16x16x32_bf16 v[26:29], v[224:227], v[216:219], v[26:29]
	ds_read_b128 v[208:211], v206 offset:2048
	v_mfma_f32_16x16x32_bf16 v[146:149], v[228:231], v[194:197], v[146:149]
	ds_read_b128 v[224:227], v207 offset:34816
	v_mfma_f32_16x16x32_bf16 v[86:89], v[228:231], v[198:201], v[86:89]
	v_mfma_f32_16x16x32_bf16 v[54:57], v[228:231], v[202:205], v[54:57]
	v_mfma_f32_16x16x32_bf16 v[22:25], v[228:231], v[216:219], v[22:25]
	ds_read_b128 v[212:215], v206 offset:4096
	v_mfma_f32_16x16x32_bf16 v[126:129], v[232:235], v[194:197], v[126:129]
	ds_read_b128 v[228:231], v207 offset:36864
	v_mfma_f32_16x16x32_bf16 v[82:85], v[232:235], v[198:201], v[82:85]
	v_mfma_f32_16x16x32_bf16 v[50:53], v[232:235], v[202:205], v[50:53]
	v_mfma_f32_16x16x32_bf16 v[18:21], v[232:235], v[216:219], v[18:21]
	v_mfma_f32_16x16x32_bf16 v[110:113], v[236:239], v[194:197], v[110:113]
	ds_read_b128 v[232:235], v207 offset:38912
	v_mfma_f32_16x16x32_bf16 v[78:81], v[236:239], v[198:201], v[78:81]
	v_mfma_f32_16x16x32_bf16 v[46:49], v[236:239], v[202:205], v[46:49]
	v_mfma_f32_16x16x32_bf16 v[14:17], v[236:239], v[216:219], v[14:17]
	v_mfma_f32_16x16x32_bf16 v[106:109], v[240:243], v[194:197], v[106:109]
	ds_read_b128 v[236:239], v207 offset:40960
	v_mfma_f32_16x16x32_bf16 v[74:77], v[240:243], v[198:201], v[74:77]
	v_mfma_f32_16x16x32_bf16 v[42:45], v[240:243], v[202:205], v[42:45]
	v_mfma_f32_16x16x32_bf16 v[10:13], v[240:243], v[216:219], v[10:13]
	v_mfma_f32_16x16x32_bf16 v[102:105], v[244:247], v[194:197], v[102:105]
	ds_read_b128 v[240:243], v207 offset:43008
	v_mfma_f32_16x16x32_bf16 v[70:73], v[244:247], v[198:201], v[70:73]
	v_mfma_f32_16x16x32_bf16 v[38:41], v[244:247], v[202:205], v[38:41]
	v_mfma_f32_16x16x32_bf16 v[6:9], v[244:247], v[216:219], v[6:9]
	s_waitcnt lgkmcnt(9)
	v_mfma_f32_16x16x32_bf16 v[2:5], v[248:251], v[216:219], v[2:5]
	ds_read_b128 v[244:247], v207 offset:45056
	ds_read_b128 v[216:219], v206 offset:6144
	v_mfma_f32_16x16x32_bf16 v[98:101], v[248:251], v[194:197], v[98:101]
	v_mfma_f32_16x16x32_bf16 v[66:69], v[248:251], v[198:201], v[66:69]
	v_mfma_f32_16x16x32_bf16 v[34:37], v[248:251], v[202:205], v[34:37]
	ds_read_b128 v[248:251], v207 offset:47104
	s_cmp_lg_u32 s7, 16
	s_mov_b32 s5, s8
	s_mov_b32 s6, s7
	s_cbranch_scc1 .LBB0_713
	s_waitcnt vmcnt(0) lgkmcnt(0)
	v_mov_b32_e32 v170, 0x358637bd
	v_mov_b32_e32 v194, 0x25a08
	v_mbcnt_lo_u32_b32 v195, -1, 0
	v_mbcnt_hi_u32_b32 v196, -1, v195
	v_mov_b32_e32 v197, 0x24000
	v_mov_b32_e32 v198, 0x1fa0
	v_mov_b32_e32 v199, 0x41b17218
	v_mov_b32_e32 v200, 0x7e800
	v_mov_b32_e32 v201, 0xfd0
	v_mov_b32_e32 v202, 0x100
	v_mov_b32_e32 v203, 0x200
	v_mov_b32_e32 v204, 0x7f61b1e6
	v_mov_b32_e32 v205, 0xff800000
	v_mov_b32_e32 v206, 0x3f80
	v_mov_b32_e32 v207, 0x1d400
	v_mov_b32_e32 v0, v171
	s_waitcnt vmcnt(7)
	v_mov_b32_e32 v115, v171
	s_barrier
	s_waitcnt vmcnt(5)
	v_mov_b64_e32 v[118:119], s[60:61]
	v_ashrrev_i32_e32 v114, 1, v115
	v_and_b32_e32 v114, 0xffffffc0, v114
	v_add_u32_e32 v114, s1, v114
	v_and_or_b32 v114, v0, 15, v114
	v_lshlrev_b32_e32 v115, 1, v115
	v_lshrrev_b32_e32 v0, 2, v0
	v_and_b32_e32 v115, 0x80, v115
	v_and_b32_e32 v0, 12, v0
	v_or3_b32 v115, v0, v115, s0
	v_mad_i64_i32 v[116:117], s[0:1], v114, s59, v[118:119]
	v_lshlrev_b32_e32 v0, 1, v115
	v_lshl_add_u64 v[124:125], v[116:117], 0, v[0:1]
	global_load_dwordx2 v[120:121], v[124:125], off
	v_lshlrev_b32_e32 v116, 2, v115
	v_ashrrev_i32_e32 v115, 31, v114
	v_lshlrev_b64 v[122:123], 12, v[114:115]
	v_mov_b32_e32 v117, v1
	v_lshl_add_u64 v[122:123], s[86:87], 0, v[122:123]
	s_waitcnt vmcnt(4)
	v_lshl_add_u64 v[130:131], v[122:123], 0, v[116:117]
	s_add_i32 s4, s4, 1
	s_waitcnt vmcnt(0)
	v_lshlrev_b32_e32 v122, 16, v120
	v_and_b32_e32 v123, 0xffff0000, v120
	v_lshlrev_b32_e32 v132, 16, v121
	v_and_b32_e32 v133, 0xffff0000, v121
	v_pk_fma_f32 v[120:121], v[122:123], s[74:75], v[158:159] op_sel_hi:[1,0,1]
	v_pk_fma_f32 v[122:123], v[132:133], s[74:75], v[160:161] op_sel_hi:[1,0,1]
	global_store_dwordx4 v[130:131], v[120:123], off
	global_load_dwordx2 v[120:121], v[124:125], off offset:32
	s_waitcnt vmcnt(0)
	v_lshlrev_b32_e32 v132, 16, v121
	v_lshlrev_b32_e32 v122, 16, v120
	v_and_b32_e32 v123, 0xffff0000, v120
	v_and_b32_e32 v133, 0xffff0000, v121
	v_pk_fma_f32 v[120:121], v[122:123], s[74:75], v[150:151] op_sel_hi:[1,0,1]
	v_pk_fma_f32 v[122:123], v[132:133], s[74:75], v[152:153] op_sel_hi:[1,0,1]
	global_store_dwordx4 v[130:131], v[120:123], off offset:64
	global_load_dwordx2 v[120:121], v[124:125], off offset:64
	s_waitcnt vmcnt(0)
	v_lshlrev_b32_e32 v132, 16, v121
	v_lshlrev_b32_e32 v122, 16, v120
	v_and_b32_e32 v123, 0xffff0000, v120
	v_and_b32_e32 v133, 0xffff0000, v121
	v_pk_fma_f32 v[120:121], v[122:123], s[74:75], v[146:147] op_sel_hi:[1,0,1]
	v_pk_fma_f32 v[122:123], v[132:133], s[74:75], v[148:149] op_sel_hi:[1,0,1]
	global_store_dwordx4 v[130:131], v[120:123], off offset:128
	global_load_dwordx2 v[120:121], v[124:125], off offset:96
	s_waitcnt vmcnt(0)
;   __device__ __forceinline__ u16* XB() const { return (u16*)(ws + O_XB); }
; DI float bflo(u32 v) { return __uint_as_float(v << 16); }
; DI float bfhi(u32 v) { return __uint_as_float(v & 0xffff0000u); }
; #define EPI_LOOP(MT_, NT_)                                                \
;   const int l_ = ltid() & 63, w_ = ltid() >> 6;                           \
;   const int wm_ = w_ >> 1, wn_ = w_ & 1, fr_ = l_ & 15, fq_ = l_ >> 4;    \
;   _Pragma("unroll") for (int mi = 0; mi < MT_; ++mi)                      \
;   _Pragma("unroll") for (int ni = 0; ni < NT_; ++ni)
; DI void phase_resgemm(const Params& p, const u16* A, int lda, const u16* W, int ldw, int K, char* smem) {
;     ...
;     EPI_LOOP(4, 8) {
;       const int row = r0 + wm_ * 64 + mi * 16 + fr_, col = c0 + wn_ * 128 + ni * 16 + fq_ * 4;
;       const uint2 xb = *(const uint2*)(p.XB() + (size_t)row * LDX + col);
;       float4 o;
;       o.x = DN_ALPHA * bflo(xb.x) + acc[mi][ni][0]; o.y = DN_ALPHA * bfhi(xb.x) + acc[mi][ni][1];
;       o.z = DN_ALPHA * bflo(xb.y) + acc[mi][ni][2]; o.w = DN_ALPHA * bfhi(xb.y) + acc[mi][ni][3];
;       *(float4*)(p.out + (size_t)row * 1024 + col) = o;
	v_lshlrev_b32_e32 v132, 16, v121
	v_lshlrev_b32_e32 v122, 16, v120
	v_and_b32_e32 v123, 0xffff0000, v120
	v_and_b32_e32 v133, 0xffff0000, v121
	v_pk_fma_f32 v[120:121], v[122:123], s[74:75], v[126:127] op_sel_hi:[1,0,1]
	v_pk_fma_f32 v[122:123], v[132:133], s[74:75], v[128:129] op_sel_hi:[1,0,1]
	global_store_dwordx4 v[130:131], v[120:123], off offset:192
	global_load_dwordx2 v[120:121], v[124:125], off offset:128
	s_waitcnt vmcnt(0)
	v_lshlrev_b32_e32 v122, 16, v120
	v_and_b32_e32 v123, 0xffff0000, v120
	v_lshlrev_b32_e32 v120, 16, v121
	v_and_b32_e32 v121, 0xffff0000, v121
	v_pk_fma_f32 v[110:111], v[122:123], s[74:75], v[110:111] op_sel_hi:[1,0,1]
	v_pk_fma_f32 v[112:113], v[120:121], s[74:75], v[112:113] op_sel_hi:[1,0,1]
	global_store_dwordx4 v[130:131], v[110:113], off offset:256
	global_load_dwordx2 v[110:111], v[124:125], off offset:160
	s_waitcnt vmcnt(0)
	v_lshlrev_b32_e32 v112, 16, v110
	v_and_b32_e32 v113, 0xffff0000, v110
	v_lshlrev_b32_e32 v110, 16, v111
	v_and_b32_e32 v111, 0xffff0000, v111
	v_pk_fma_f32 v[106:107], v[112:113], s[74:75], v[106:107] op_sel_hi:[1,0,1]
	v_pk_fma_f32 v[108:109], v[110:111], s[74:75], v[108:109] op_sel_hi:[1,0,1]
	global_store_dwordx4 v[130:131], v[106:109], off offset:320
	global_load_dwordx2 v[106:107], v[124:125], off offset:192
	s_waitcnt vmcnt(0)
	v_lshlrev_b32_e32 v108, 16, v106
	v_and_b32_e32 v109, 0xffff0000, v106
	v_lshlrev_b32_e32 v106, 16, v107
	v_and_b32_e32 v107, 0xffff0000, v107
	v_pk_fma_f32 v[102:103], v[108:109], s[74:75], v[102:103] op_sel_hi:[1,0,1]
	v_pk_fma_f32 v[104:105], v[106:107], s[74:75], v[104:105] op_sel_hi:[1,0,1]
	global_store_dwordx4 v[130:131], v[102:105], off offset:384
	global_load_dwordx2 v[102:103], v[124:125], off offset:224
	s_waitcnt vmcnt(0)
	v_lshlrev_b32_e32 v108, 16, v102
	v_or_b32_e32 v104, 16, v114
	v_and_b32_e32 v109, 0xffff0000, v102
	v_lshlrev_b32_e32 v102, 16, v103
	v_and_b32_e32 v103, 0xffff0000, v103
	v_mad_i64_i32 v[106:107], s[0:1], v104, s59, v[118:119]
	v_pk_fma_f32 v[98:99], v[108:109], s[74:75], v[98:99] op_sel_hi:[1,0,1]
	v_pk_fma_f32 v[100:101], v[102:103], s[74:75], v[100:101] op_sel_hi:[1,0,1]
	v_lshl_add_u64 v[106:107], v[106:107], 0, v[0:1]
	global_store_dwordx4 v[130:131], v[98:101], off offset:448
	global_load_dwordx2 v[98:99], v[106:107], off
	v_ashrrev_i32_e32 v105, 31, v104
	v_lshlrev_b64 v[100:101], 12, v[104:105]
	v_lshl_add_u64 v[100:101], s[86:87], 0, v[100:101]
	v_lshl_add_u64 v[100:101], v[100:101], 0, v[116:117]
	s_waitcnt vmcnt(0)
	v_lshlrev_b32_e32 v102, 16, v98
	v_and_b32_e32 v103, 0xffff0000, v98
	v_lshlrev_b32_e32 v98, 16, v99
	v_and_b32_e32 v99, 0xffff0000, v99
	v_pk_fma_f32 v[94:95], v[102:103], s[74:75], v[94:95] op_sel_hi:[1,0,1]
	v_pk_fma_f32 v[96:97], v[98:99], s[74:75], v[96:97] op_sel_hi:[1,0,1]
	global_store_dwordx4 v[100:101], v[94:97], off
	global_load_dwordx2 v[94:95], v[106:107], off offset:32
	s_waitcnt vmcnt(0)
	v_lshlrev_b32_e32 v96, 16, v94
	v_and_b32_e32 v97, 0xffff0000, v94
	v_lshlrev_b32_e32 v94, 16, v95
	v_and_b32_e32 v95, 0xffff0000, v95
	v_pk_fma_f32 v[90:91], v[96:97], s[74:75], v[90:91] op_sel_hi:[1,0,1]
	v_pk_fma_f32 v[92:93], v[94:95], s[74:75], v[92:93] op_sel_hi:[1,0,1]
	global_store_dwordx4 v[100:101], v[90:93], off offset:64
	global_load_dwordx2 v[90:91], v[106:107], off offset:64
	s_waitcnt vmcnt(0)
	v_lshlrev_b32_e32 v92, 16, v90
	v_and_b32_e32 v93, 0xffff0000, v90
	v_lshlrev_b32_e32 v90, 16, v91
	v_and_b32_e32 v91, 0xffff0000, v91
	v_pk_fma_f32 v[86:87], v[92:93], s[74:75], v[86:87] op_sel_hi:[1,0,1]
	v_pk_fma_f32 v[88:89], v[90:91], s[74:75], v[88:89] op_sel_hi:[1,0,1]
	global_store_dwordx4 v[100:101], v[86:89], off offset:128
	global_load_dwordx2 v[86:87], v[106:107], off offset:96
	s_waitcnt vmcnt(0)
	v_lshlrev_b32_e32 v88, 16, v86
	v_and_b32_e32 v89, 0xffff0000, v86
	v_lshlrev_b32_e32 v86, 16, v87
	v_and_b32_e32 v87, 0xffff0000, v87
	v_pk_fma_f32 v[82:83], v[88:89], s[74:75], v[82:83] op_sel_hi:[1,0,1]
	v_pk_fma_f32 v[84:85], v[86:87], s[74:75], v[84:85] op_sel_hi:[1,0,1]
	global_store_dwordx4 v[100:101], v[82:85], off offset:192
	global_load_dwordx2 v[82:83], v[106:107], off offset:128
	s_waitcnt vmcnt(0)
	v_lshlrev_b32_e32 v84, 16, v82
	v_and_b32_e32 v85, 0xffff0000, v82
	v_lshlrev_b32_e32 v82, 16, v83
	v_and_b32_e32 v83, 0xffff0000, v83
	v_pk_fma_f32 v[78:79], v[84:85], s[74:75], v[78:79] op_sel_hi:[1,0,1]
	v_pk_fma_f32 v[80:81], v[82:83], s[74:75], v[80:81] op_sel_hi:[1,0,1]
	global_store_dwordx4 v[100:101], v[78:81], off offset:256
	global_load_dwordx2 v[78:79], v[106:107], off offset:160
	s_waitcnt vmcnt(0)
	v_lshlrev_b32_e32 v80, 16, v78
	v_and_b32_e32 v81, 0xffff0000, v78
	v_lshlrev_b32_e32 v78, 16, v79
	v_and_b32_e32 v79, 0xffff0000, v79
	v_pk_fma_f32 v[74:75], v[80:81], s[74:75], v[74:75] op_sel_hi:[1,0,1]
	v_pk_fma_f32 v[76:77], v[78:79], s[74:75], v[76:77] op_sel_hi:[1,0,1]
	global_store_dwordx4 v[100:101], v[74:77], off offset:320
	global_load_dwordx2 v[74:75], v[106:107], off offset:192
	s_waitcnt vmcnt(0)
	v_lshlrev_b32_e32 v76, 16, v74
	v_and_b32_e32 v77, 0xffff0000, v74
	v_lshlrev_b32_e32 v74, 16, v75
	v_and_b32_e32 v75, 0xffff0000, v75
	v_pk_fma_f32 v[70:71], v[76:77], s[74:75], v[70:71] op_sel_hi:[1,0,1]
	v_pk_fma_f32 v[72:73], v[74:75], s[74:75], v[72:73] op_sel_hi:[1,0,1]
	global_store_dwordx4 v[100:101], v[70:73], off offset:384
	global_load_dwordx2 v[70:71], v[106:107], off offset:224
	s_waitcnt vmcnt(0)
;   __device__ __forceinline__ u16* XB() const { return (u16*)(ws + O_XB); }
; DI float bflo(u32 v) { return __uint_as_float(v << 16); }
; DI float bfhi(u32 v) { return __uint_as_float(v & 0xffff0000u); }
; #define EPI_LOOP(MT_, NT_)                                                \
;   const int l_ = ltid() & 63, w_ = ltid() >> 6;                           \
;   const int wm_ = w_ >> 1, wn_ = w_ & 1, fr_ = l_ & 15, fq_ = l_ >> 4;    \
;   _Pragma("unroll") for (int mi = 0; mi < MT_; ++mi)                      \
;   _Pragma("unroll") for (int ni = 0; ni < NT_; ++ni)
; DI void phase_resgemm(const Params& p, const u16* A, int lda, const u16* W, int ldw, int K, char* smem) {
;     ...
;     EPI_LOOP(4, 8) {
;       const int row = r0 + wm_ * 64 + mi * 16 + fr_, col = c0 + wn_ * 128 + ni * 16 + fq_ * 4;
;       const uint2 xb = *(const uint2*)(p.XB() + (size_t)row * LDX + col);
;       float4 o;
;       o.x = DN_ALPHA * bflo(xb.x) + acc[mi][ni][0]; o.y = DN_ALPHA * bfhi(xb.x) + acc[mi][ni][1];
;       o.z = DN_ALPHA * bflo(xb.y) + acc[mi][ni][2]; o.w = DN_ALPHA * bfhi(xb.y) + acc[mi][ni][3];
;       *(float4*)(p.out + (size_t)row * 1024 + col) = o;
	v_lshlrev_b32_e32 v76, 16, v70
	v_or_b32_e32 v72, 32, v114
	v_and_b32_e32 v77, 0xffff0000, v70
	v_lshlrev_b32_e32 v70, 16, v71
	v_and_b32_e32 v71, 0xffff0000, v71
	v_mad_i64_i32 v[74:75], s[0:1], v72, s59, v[118:119]
	v_pk_fma_f32 v[66:67], v[76:77], s[74:75], v[66:67] op_sel_hi:[1,0,1]
	v_pk_fma_f32 v[68:69], v[70:71], s[74:75], v[68:69] op_sel_hi:[1,0,1]
	v_lshl_add_u64 v[74:75], v[74:75], 0, v[0:1]
	global_store_dwordx4 v[100:101], v[66:69], off offset:448
	global_load_dwordx2 v[66:67], v[74:75], off
	v_ashrrev_i32_e32 v73, 31, v72
	v_lshlrev_b64 v[68:69], 12, v[72:73]
	v_lshl_add_u64 v[68:69], s[86:87], 0, v[68:69]
	v_lshl_add_u64 v[68:69], v[68:69], 0, v[116:117]
	s_waitcnt vmcnt(0)
	v_lshlrev_b32_e32 v70, 16, v66
	v_and_b32_e32 v71, 0xffff0000, v66
	v_lshlrev_b32_e32 v66, 16, v67
	v_and_b32_e32 v67, 0xffff0000, v67
	v_pk_fma_f32 v[62:63], v[70:71], s[74:75], v[62:63] op_sel_hi:[1,0,1]
	v_pk_fma_f32 v[64:65], v[66:67], s[74:75], v[64:65] op_sel_hi:[1,0,1]
	global_store_dwordx4 v[68:69], v[62:65], off
	global_load_dwordx2 v[62:63], v[74:75], off offset:32
	s_waitcnt vmcnt(0)
	v_lshlrev_b32_e32 v64, 16, v62
	v_and_b32_e32 v65, 0xffff0000, v62
	v_lshlrev_b32_e32 v62, 16, v63
	v_and_b32_e32 v63, 0xffff0000, v63
	v_pk_fma_f32 v[58:59], v[64:65], s[74:75], v[58:59] op_sel_hi:[1,0,1]
	v_pk_fma_f32 v[60:61], v[62:63], s[74:75], v[60:61] op_sel_hi:[1,0,1]
	global_store_dwordx4 v[68:69], v[58:61], off offset:64
	global_load_dwordx2 v[58:59], v[74:75], off offset:64
	s_waitcnt vmcnt(0)
	v_lshlrev_b32_e32 v60, 16, v58
	v_and_b32_e32 v61, 0xffff0000, v58
	v_lshlrev_b32_e32 v58, 16, v59
	v_and_b32_e32 v59, 0xffff0000, v59
	v_pk_fma_f32 v[54:55], v[60:61], s[74:75], v[54:55] op_sel_hi:[1,0,1]
	v_pk_fma_f32 v[56:57], v[58:59], s[74:75], v[56:57] op_sel_hi:[1,0,1]
	global_store_dwordx4 v[68:69], v[54:57], off offset:128
	global_load_dwordx2 v[54:55], v[74:75], off offset:96
	s_waitcnt vmcnt(0)
	v_lshlrev_b32_e32 v56, 16, v54
	v_and_b32_e32 v57, 0xffff0000, v54
	v_lshlrev_b32_e32 v54, 16, v55
	v_and_b32_e32 v55, 0xffff0000, v55
	v_pk_fma_f32 v[50:51], v[56:57], s[74:75], v[50:51] op_sel_hi:[1,0,1]
	v_pk_fma_f32 v[52:53], v[54:55], s[74:75], v[52:53] op_sel_hi:[1,0,1]
	global_store_dwordx4 v[68:69], v[50:53], off offset:192
	global_load_dwordx2 v[50:51], v[74:75], off offset:128
	s_waitcnt vmcnt(0)
	v_lshlrev_b32_e32 v52, 16, v50
	v_and_b32_e32 v53, 0xffff0000, v50
	v_lshlrev_b32_e32 v50, 16, v51
	v_and_b32_e32 v51, 0xffff0000, v51
	v_pk_fma_f32 v[46:47], v[52:53], s[74:75], v[46:47] op_sel_hi:[1,0,1]
	v_pk_fma_f32 v[48:49], v[50:51], s[74:75], v[48:49] op_sel_hi:[1,0,1]
	global_store_dwordx4 v[68:69], v[46:49], off offset:256
	global_load_dwordx2 v[46:47], v[74:75], off offset:160
	s_waitcnt vmcnt(0)
	v_lshlrev_b32_e32 v48, 16, v46
	v_and_b32_e32 v49, 0xffff0000, v46
	v_lshlrev_b32_e32 v46, 16, v47
	v_and_b32_e32 v47, 0xffff0000, v47
	v_pk_fma_f32 v[42:43], v[48:49], s[74:75], v[42:43] op_sel_hi:[1,0,1]
	v_pk_fma_f32 v[44:45], v[46:47], s[74:75], v[44:45] op_sel_hi:[1,0,1]
	global_store_dwordx4 v[68:69], v[42:45], off offset:320
	global_load_dwordx2 v[42:43], v[74:75], off offset:192
	s_waitcnt vmcnt(0)
	v_lshlrev_b32_e32 v44, 16, v42
	v_and_b32_e32 v45, 0xffff0000, v42
	v_lshlrev_b32_e32 v42, 16, v43
	v_and_b32_e32 v43, 0xffff0000, v43
	v_pk_fma_f32 v[38:39], v[44:45], s[74:75], v[38:39] op_sel_hi:[1,0,1]
	v_pk_fma_f32 v[40:41], v[42:43], s[74:75], v[40:41] op_sel_hi:[1,0,1]
	global_store_dwordx4 v[68:69], v[38:41], off offset:384
	global_load_dwordx2 v[38:39], v[74:75], off offset:224
	s_waitcnt vmcnt(0)
;   __device__ __forceinline__ u16* XB() const { return (u16*)(ws + O_XB); }
; DI float bflo(u32 v) { return __uint_as_float(v << 16); }
; DI float bfhi(u32 v) { return __uint_as_float(v & 0xffff0000u); }
; #define EPI_LOOP(MT_, NT_)                                                \
;   const int l_ = ltid() & 63, w_ = ltid() >> 6;                           \
;   const int wm_ = w_ >> 1, wn_ = w_ & 1, fr_ = l_ & 15, fq_ = l_ >> 4;    \
;   _Pragma("unroll") for (int mi = 0; mi < MT_; ++mi)                      \
;   _Pragma("unroll") for (int ni = 0; ni < NT_; ++ni)
; DI void phase_resgemm(const Params& p, const u16* A, int lda, const u16* W, int ldw, int K, char* smem) {
;     ...
;     EPI_LOOP(4, 8) {
;       const int row = r0 + wm_ * 64 + mi * 16 + fr_, col = c0 + wn_ * 128 + ni * 16 + fq_ * 4;
;       const uint2 xb = *(const uint2*)(p.XB() + (size_t)row * LDX + col);
;       float4 o;
;       o.x = DN_ALPHA * bflo(xb.x) + acc[mi][ni][0]; o.y = DN_ALPHA * bfhi(xb.x) + acc[mi][ni][1];
;       o.z = DN_ALPHA * bflo(xb.y) + acc[mi][ni][2]; o.w = DN_ALPHA * bfhi(xb.y) + acc[mi][ni][3];
;       *(float4*)(p.out + (size_t)row * 1024 + col) = o;
	v_lshlrev_b32_e32 v44, 16, v38
	v_or_b32_e32 v40, 48, v114
	v_and_b32_e32 v45, 0xffff0000, v38
	v_lshlrev_b32_e32 v38, 16, v39
	v_and_b32_e32 v39, 0xffff0000, v39
	v_mad_i64_i32 v[42:43], s[0:1], v40, s59, v[118:119]
	v_pk_fma_f32 v[34:35], v[44:45], s[74:75], v[34:35] op_sel_hi:[1,0,1]
	v_pk_fma_f32 v[36:37], v[38:39], s[74:75], v[36:37] op_sel_hi:[1,0,1]
	v_lshl_add_u64 v[42:43], v[42:43], 0, v[0:1]
	global_store_dwordx4 v[68:69], v[34:37], off offset:448
	global_load_dwordx2 v[34:35], v[42:43], off
	v_ashrrev_i32_e32 v41, 31, v40
	v_lshlrev_b64 v[36:37], 12, v[40:41]
	v_lshl_add_u64 v[36:37], s[86:87], 0, v[36:37]
	v_lshl_add_u64 v[36:37], v[36:37], 0, v[116:117]
	s_mov_b64 s[0:1], 0
	s_waitcnt vmcnt(0)
	v_lshlrev_b32_e32 v38, 16, v34
	v_and_b32_e32 v39, 0xffff0000, v34
	v_lshlrev_b32_e32 v34, 16, v35
	v_and_b32_e32 v35, 0xffff0000, v35
	v_pk_fma_f32 v[30:31], v[38:39], s[74:75], v[30:31] op_sel_hi:[1,0,1]
	v_pk_fma_f32 v[32:33], v[34:35], s[74:75], v[32:33] op_sel_hi:[1,0,1]
	global_store_dwordx4 v[36:37], v[30:33], off
	global_load_dwordx2 v[30:31], v[42:43], off offset:32
	s_waitcnt vmcnt(0)
	v_lshlrev_b32_e32 v32, 16, v30
	v_and_b32_e32 v33, 0xffff0000, v30
	v_lshlrev_b32_e32 v30, 16, v31
	v_and_b32_e32 v31, 0xffff0000, v31
	v_pk_fma_f32 v[26:27], v[32:33], s[74:75], v[26:27] op_sel_hi:[1,0,1]
	v_pk_fma_f32 v[28:29], v[30:31], s[74:75], v[28:29] op_sel_hi:[1,0,1]
	global_store_dwordx4 v[36:37], v[26:29], off offset:64
	global_load_dwordx2 v[26:27], v[42:43], off offset:64
	s_waitcnt vmcnt(0)
	v_lshlrev_b32_e32 v28, 16, v26
	v_and_b32_e32 v29, 0xffff0000, v26
	v_lshlrev_b32_e32 v26, 16, v27
	v_and_b32_e32 v27, 0xffff0000, v27
	v_pk_fma_f32 v[22:23], v[28:29], s[74:75], v[22:23] op_sel_hi:[1,0,1]
	v_pk_fma_f32 v[24:25], v[26:27], s[74:75], v[24:25] op_sel_hi:[1,0,1]
	global_store_dwordx4 v[36:37], v[22:25], off offset:128
	global_load_dwordx2 v[22:23], v[42:43], off offset:96
	s_waitcnt vmcnt(0)
	v_lshlrev_b32_e32 v24, 16, v22
	v_and_b32_e32 v25, 0xffff0000, v22
	v_lshlrev_b32_e32 v22, 16, v23
	v_and_b32_e32 v23, 0xffff0000, v23
	v_pk_fma_f32 v[18:19], v[24:25], s[74:75], v[18:19] op_sel_hi:[1,0,1]
	v_pk_fma_f32 v[20:21], v[22:23], s[74:75], v[20:21] op_sel_hi:[1,0,1]
	global_store_dwordx4 v[36:37], v[18:21], off offset:192
	global_load_dwordx2 v[18:19], v[42:43], off offset:128
	s_waitcnt vmcnt(0)
	v_lshlrev_b32_e32 v20, 16, v18
	v_and_b32_e32 v21, 0xffff0000, v18
	v_lshlrev_b32_e32 v18, 16, v19
	v_and_b32_e32 v19, 0xffff0000, v19
	v_pk_fma_f32 v[14:15], v[20:21], s[74:75], v[14:15] op_sel_hi:[1,0,1]
	v_pk_fma_f32 v[16:17], v[18:19], s[74:75], v[16:17] op_sel_hi:[1,0,1]
	global_store_dwordx4 v[36:37], v[14:17], off offset:256
	global_load_dwordx2 v[14:15], v[42:43], off offset:160
	s_waitcnt vmcnt(0)
	v_lshlrev_b32_e32 v16, 16, v14
	v_and_b32_e32 v17, 0xffff0000, v14
	v_lshlrev_b32_e32 v14, 16, v15
	v_and_b32_e32 v15, 0xffff0000, v15
	v_pk_fma_f32 v[10:11], v[16:17], s[74:75], v[10:11] op_sel_hi:[1,0,1]
	v_pk_fma_f32 v[12:13], v[14:15], s[74:75], v[12:13] op_sel_hi:[1,0,1]
	global_store_dwordx4 v[36:37], v[10:13], off offset:320
	global_load_dwordx2 v[10:11], v[42:43], off offset:192
	s_waitcnt vmcnt(0)
	v_lshlrev_b32_e32 v12, 16, v10
	v_and_b32_e32 v13, 0xffff0000, v10
	v_lshlrev_b32_e32 v10, 16, v11
	v_and_b32_e32 v11, 0xffff0000, v11
	v_pk_fma_f32 v[6:7], v[12:13], s[74:75], v[6:7] op_sel_hi:[1,0,1]
	v_pk_fma_f32 v[8:9], v[10:11], s[74:75], v[8:9] op_sel_hi:[1,0,1]
	global_store_dwordx4 v[36:37], v[6:9], off offset:384
	global_load_dwordx2 v[6:7], v[42:43], off offset:224
	s_waitcnt vmcnt(0)
	v_lshlrev_b32_e32 v8, 16, v6
	v_and_b32_e32 v9, 0xffff0000, v6
	v_lshlrev_b32_e32 v6, 16, v7
	v_and_b32_e32 v7, 0xffff0000, v7
	v_pk_fma_f32 v[2:3], v[8:9], s[74:75], v[2:3] op_sel_hi:[1,0,1]
	v_pk_fma_f32 v[4:5], v[6:7], s[74:75], v[4:5] op_sel_hi:[1,0,1]
	global_store_dwordx4 v[36:37], v[2:5], off offset:448
	s_branch .LBB0_710

; DI f32x4 mfma16(bf16x8 a, bf16x8 b, f32x4 c) { return __builtin_amdgcn_mfma_f32_16x16x32_bf16(a, b, c, 0, 0, 0); }
; #define GLOAD(kt) { GL1(0, kt) GL1(1, kt) GL1(2, kt) GL1(3, kt) }
; #define SSTORE(buf)                              \
;   {                                              \
;     char* as_ = smem + (buf) * BUF;              \
;     char* bs_ = as_ + ASZ;                       \
;     SS1(0) SS1(1) SS1(2) SS1(3)                  \
;   }
; template <int MT, int NT>
; DI void gemm_core(const u16* __restrict__ A, int lda, const u16* __restrict__ B, int ldb, int K,
;                   f32x4 (&acc)[MT][NT], char* smem) {
;     ...
;   for (int kt = 0; kt < nk; ++kt) {
;     __syncthreads();
;     SSTORE((kt + 1) & 1);
;     { const int kn_ = (kt + 2 < nk) ? kt + 2 : nk - 1; GLOAD(kn_); }
;     const char* as = smem + (kt & 1) * BUF;
;     const char* bs = as + ASZ;
; #pragma unroll
;     for (int kk = 0; kk < 2; ++kk) {
;       bf16x8 xf[MT], wf[NT];
; #pragma unroll
;       for (int mi = 0; mi < MT; ++mi)
;         xf[mi] = *(const bf16x8*)(as + (wm * (MT * 16) + mi * 16 + fr) * 128 + (((kk * 4 + fq) ^ fsw) * 16));
; #pragma unroll
;       for (int ni = 0; ni < NT; ++ni)
;         wf[ni] = *(const bf16x8*)(bs + (wn * (NT * 16) + ni * 16 + fr) * 128 + (((kk * 4 + fq) ^ fsw) * 16));
;       __builtin_amdgcn_s_setprio(1);
; #pragma unroll
;       for (int mi = 0; mi < MT; ++mi)
; #pragma unroll
;         for (int ni = 0; ni < NT; ++ni) acc[mi][ni] = mfma16(wf[ni], xf[mi], acc[mi][ni]);
;       __builtin_amdgcn_s_setprio(0);
;     }
.LBB0_768:
	s_add_i32 s8, s5, 0x10000
	s_and_b32 s9, s8, 0x10000
	s_add_i32 s7, s6, 1
	s_min_u32 s6, s6, 13
	s_lshl_b32 s54, s6, 7
	s_and_b32 s5, s5, 0x10000
	v_or_b32_e32 v206, s5, v189
	v_add_u32_e32 v207, v206, v188
	v_add_u32_e32 v206, v206, v187
	v_add3_u32 v170, s9, v0, v173
	s_waitcnt lgkmcnt(10)
	v_mfma_f32_16x16x32_bf16 v[158:161], v[220:223], v[190:193], v[158:161]
	s_waitcnt vmcnt(0)
	ds_write_b128 v170, v[110:113]
	s_waitcnt lgkmcnt(10)
	v_mfma_f32_16x16x32_bf16 v[94:97], v[220:223], v[208:211], v[94:97]
	v_lshl_add_u64 v[110:111], v[162:163], 0, s[54:55]
	global_load_dwordx4 v[110:113], v[110:111], off offset:256
	s_waitcnt lgkmcnt(8)
	v_mfma_f32_16x16x32_bf16 v[62:65], v[220:223], v[212:215], v[62:65]
	ds_write_b128 v170, v[118:121] offset:32768
	s_waitcnt lgkmcnt(3)
	v_mfma_f32_16x16x32_bf16 v[30:33], v[220:223], v[216:219], v[30:33]
	v_lshl_add_u64 v[118:119], v[164:165], 0, s[54:55]
	global_load_dwordx4 v[118:121], v[118:119], off offset:256
	ds_read_b128 v[194:197], v206
	v_mfma_f32_16x16x32_bf16 v[154:157], v[224:227], v[190:193], v[154:157]
	ds_read_b128 v[220:223], v207 offset:32768
	ds_write_b128 v170, v[114:117] offset:8192
	v_mfma_f32_16x16x32_bf16 v[90:93], v[224:227], v[208:211], v[90:93]
	v_lshl_add_u64 v[114:115], v[166:167], 0, s[54:55]
	global_load_dwordx4 v[114:117], v[114:115], off offset:256
	v_mfma_f32_16x16x32_bf16 v[58:61], v[224:227], v[212:215], v[58:61]
	v_mfma_f32_16x16x32_bf16 v[26:29], v[224:227], v[216:219], v[26:29]
	ds_read_b128 v[198:201], v206 offset:2048
	v_mfma_f32_16x16x32_bf16 v[146:149], v[228:231], v[190:193], v[146:149]
	ds_read_b128 v[224:227], v207 offset:34816
	ds_write_b128 v170, v[126:129] offset:40960
	v_mfma_f32_16x16x32_bf16 v[86:89], v[228:231], v[208:211], v[86:89]
	v_lshl_add_u64 v[126:127], v[168:169], 0, s[54:55]
	global_load_dwordx4 v[126:129], v[126:127], off offset:256
	v_mfma_f32_16x16x32_bf16 v[54:57], v[228:231], v[212:215], v[54:57]
	v_mfma_f32_16x16x32_bf16 v[22:25], v[228:231], v[216:219], v[22:25]
	ds_read_b128 v[202:205], v206 offset:4096
	v_mfma_f32_16x16x32_bf16 v[142:145], v[232:235], v[190:193], v[142:145]
	ds_read_b128 v[228:231], v207 offset:36864
	ds_write_b128 v170, v[122:125] offset:16384
	v_mfma_f32_16x16x32_bf16 v[82:85], v[232:235], v[208:211], v[82:85]
	v_lshl_add_u64 v[122:123], v[176:177], 0, s[54:55]
	global_load_dwordx4 v[122:125], v[122:123], off offset:256
	v_mfma_f32_16x16x32_bf16 v[50:53], v[232:235], v[212:215], v[50:53]
	v_mfma_f32_16x16x32_bf16 v[18:21], v[232:235], v[216:219], v[18:21]
	v_mfma_f32_16x16x32_bf16 v[138:141], v[236:239], v[190:193], v[138:141]
	ds_read_b128 v[232:235], v207 offset:38912
	ds_write_b128 v170, v[134:137] offset:49152
	v_mfma_f32_16x16x32_bf16 v[78:81], v[236:239], v[208:211], v[78:81]
	v_lshl_add_u64 v[134:135], v[178:179], 0, s[54:55]
	global_load_dwordx4 v[134:137], v[134:135], off offset:256
	v_mfma_f32_16x16x32_bf16 v[46:49], v[236:239], v[212:215], v[46:49]
	v_mfma_f32_16x16x32_bf16 v[14:17], v[236:239], v[216:219], v[14:17]
	v_mfma_f32_16x16x32_bf16 v[106:109], v[240:243], v[190:193], v[106:109]
	ds_read_b128 v[236:239], v207 offset:40960
	ds_write_b128 v170, v[130:133] offset:24576
	v_mfma_f32_16x16x32_bf16 v[74:77], v[240:243], v[208:211], v[74:77]
	v_lshl_add_u64 v[130:131], v[180:181], 0, s[54:55]
	global_load_dwordx4 v[130:133], v[130:131], off offset:256
	v_mfma_f32_16x16x32_bf16 v[42:45], v[240:243], v[212:215], v[42:45]
	v_mfma_f32_16x16x32_bf16 v[10:13], v[240:243], v[216:219], v[10:13]
	v_mfma_f32_16x16x32_bf16 v[102:105], v[244:247], v[190:193], v[102:105]
	ds_read_b128 v[240:243], v207 offset:43008
	ds_write_b128 v170, v[150:153] offset:57344
	v_mfma_f32_16x16x32_bf16 v[70:73], v[244:247], v[208:211], v[70:73]
	v_lshl_add_u64 v[150:151], v[182:183], 0, s[54:55]
	global_load_dwordx4 v[150:153], v[150:151], off offset:256
	v_mfma_f32_16x16x32_bf16 v[38:41], v[244:247], v[212:215], v[38:41]
	v_mfma_f32_16x16x32_bf16 v[6:9], v[244:247], v[216:219], v[6:9]
	s_waitcnt lgkmcnt(15)
	v_mfma_f32_16x16x32_bf16 v[2:5], v[248:251], v[216:219], v[2:5]
	ds_read_b128 v[244:247], v207 offset:45056
	ds_read_b128 v[216:219], v206 offset:6144
	v_mfma_f32_16x16x32_bf16 v[98:101], v[248:251], v[190:193], v[98:101]
	v_mfma_f32_16x16x32_bf16 v[66:69], v[248:251], v[208:211], v[66:69]
	v_mfma_f32_16x16x32_bf16 v[34:37], v[248:251], v[212:215], v[34:37]
	ds_read_b128 v[248:251], v207 offset:47104
	s_waitcnt lgkmcnt(3)
	s_barrier
;   __device__ __forceinline__ u16* P() const { return (u16*)(ws + O_P); }
; DI f32x4 mfma16(bf16x8 a, bf16x8 b, f32x4 c) { return __builtin_amdgcn_mfma_f32_16x16x32_bf16(a, b, c, 0, 0, 0); }
; #define EPI_LOOP(MT_, NT_)                                                \
;   const int l_ = ltid() & 63, w_ = ltid() >> 6;                           \
;   const int wm_ = w_ >> 1, wn_ = w_ & 1, fr_ = l_ & 15, fq_ = l_ >> 4;    \
;   _Pragma("unroll") for (int mi = 0; mi < MT_; ++mi)                      \
;   _Pragma("unroll") for (int ni = 0; ni < NT_; ++ni)
; template <int MT, int NT>
; DI void gemm_core(const u16* __restrict__ A, int lda, const u16* __restrict__ B, int ldb, int K,
;                   f32x4 (&acc)[MT][NT], char* smem) {
;     ...
;     for (int kk = 0; kk < 2; ++kk) {
;       bf16x8 xf[MT], wf[NT];
; #pragma unroll
;       for (int mi = 0; mi < MT; ++mi)
;         xf[mi] = *(const bf16x8*)(as + (wm * (MT * 16) + mi * 16 + fr) * 128 + (((kk * 4 + fq) ^ fsw) * 16));
; #pragma unroll
;       for (int ni = 0; ni < NT; ++ni)
;         wf[ni] = *(const bf16x8*)(bs + (wn * (NT * 16) + ni * 16 + fr) * 128 + (((kk * 4 + fq) ^ fsw) * 16));
;       __builtin_amdgcn_s_setprio(1);
; #pragma unroll
;       for (int mi = 0; mi < MT; ++mi)
; #pragma unroll
;         for (int ni = 0; ni < NT; ++ni) acc[mi][ni] = mfma16(wf[ni], xf[mi], acc[mi][ni]);
;       __builtin_amdgcn_s_setprio(0);
;     }
;   }
; DI void phase_ff1(const Params& p, int l, char* smem) {
;     ...
;     EPI_LOOP(4, 8) {
;       const int row = r0 + wm_ * 64 + mi * 16 + fr_, col = c0 + wn_ * 128 + ni * 16 + fq_ * 4;
;       float a0 = fmaxf(acc[mi][ni][0], 0.f), a1 = fmaxf(acc[mi][ni][1], 0.f), a2 = fmaxf(acc[mi][ni][2], 0.f), a3 = fmaxf(acc[mi][ni][3], 0.f);
;       uint2 o;
;       o.x = pack2(a0 * a0, a1 * a1); o.y = pack2(a2 * a2, a3 * a3);
;       *(uint2*)(p.P() + (size_t)row * LDH + col) = o;
	v_or_b32_e32 v206, s9, v186
	v_add_u32_e32 v207, v206, v188
	v_add_u32_e32 v206, v206, v187
	v_mfma_f32_16x16x32_bf16 v[158:161], v[220:223], v[194:197], v[158:161]
	v_mfma_f32_16x16x32_bf16 v[94:97], v[220:223], v[198:201], v[94:97]
	v_mfma_f32_16x16x32_bf16 v[62:65], v[220:223], v[202:205], v[62:65]
	s_waitcnt lgkmcnt(1)
	v_mfma_f32_16x16x32_bf16 v[30:33], v[220:223], v[216:219], v[30:33]
	ds_read_b128 v[190:193], v206
	v_mfma_f32_16x16x32_bf16 v[154:157], v[224:227], v[194:197], v[154:157]
	ds_read_b128 v[220:223], v207 offset:32768
	v_mfma_f32_16x16x32_bf16 v[90:93], v[224:227], v[198:201], v[90:93]
	v_mfma_f32_16x16x32_bf16 v[58:61], v[224:227], v[202:205], v[58:61]
	v_mfma_f32_16x16x32_bf16 v[26:29], v[224:227], v[216:219], v[26:29]
	ds_read_b128 v[208:211], v206 offset:2048
	v_mfma_f32_16x16x32_bf16 v[146:149], v[228:231], v[194:197], v[146:149]
	ds_read_b128 v[224:227], v207 offset:34816
	v_mfma_f32_16x16x32_bf16 v[86:89], v[228:231], v[198:201], v[86:89]
	v_mfma_f32_16x16x32_bf16 v[54:57], v[228:231], v[202:205], v[54:57]
	v_mfma_f32_16x16x32_bf16 v[22:25], v[228:231], v[216:219], v[22:25]
	ds_read_b128 v[212:215], v206 offset:4096
	v_mfma_f32_16x16x32_bf16 v[142:145], v[232:235], v[194:197], v[142:145]
	ds_read_b128 v[228:231], v207 offset:36864
	v_mfma_f32_16x16x32_bf16 v[82:85], v[232:235], v[198:201], v[82:85]
	v_mfma_f32_16x16x32_bf16 v[50:53], v[232:235], v[202:205], v[50:53]
	v_mfma_f32_16x16x32_bf16 v[18:21], v[232:235], v[216:219], v[18:21]
	v_mfma_f32_16x16x32_bf16 v[138:141], v[236:239], v[194:197], v[138:141]
	ds_read_b128 v[232:235], v207 offset:38912
	v_mfma_f32_16x16x32_bf16 v[78:81], v[236:239], v[198:201], v[78:81]
	v_mfma_f32_16x16x32_bf16 v[46:49], v[236:239], v[202:205], v[46:49]
	v_mfma_f32_16x16x32_bf16 v[14:17], v[236:239], v[216:219], v[14:17]
	v_mfma_f32_16x16x32_bf16 v[106:109], v[240:243], v[194:197], v[106:109]
	ds_read_b128 v[236:239], v207 offset:40960
	v_mfma_f32_16x16x32_bf16 v[74:77], v[240:243], v[198:201], v[74:77]
	v_mfma_f32_16x16x32_bf16 v[42:45], v[240:243], v[202:205], v[42:45]
	v_mfma_f32_16x16x32_bf16 v[10:13], v[240:243], v[216:219], v[10:13]
	v_mfma_f32_16x16x32_bf16 v[102:105], v[244:247], v[194:197], v[102:105]
	ds_read_b128 v[240:243], v207 offset:43008
	v_mfma_f32_16x16x32_bf16 v[70:73], v[244:247], v[198:201], v[70:73]
	v_mfma_f32_16x16x32_bf16 v[38:41], v[244:247], v[202:205], v[38:41]
	v_mfma_f32_16x16x32_bf16 v[6:9], v[244:247], v[216:219], v[6:9]
	s_waitcnt lgkmcnt(9)
	v_mfma_f32_16x16x32_bf16 v[2:5], v[248:251], v[216:219], v[2:5]
	ds_read_b128 v[244:247], v207 offset:45056
	ds_read_b128 v[216:219], v206 offset:6144
	v_mfma_f32_16x16x32_bf16 v[98:101], v[248:251], v[194:197], v[98:101]
	v_mfma_f32_16x16x32_bf16 v[66:69], v[248:251], v[198:201], v[66:69]
	v_mfma_f32_16x16x32_bf16 v[34:37], v[248:251], v[202:205], v[34:37]
	ds_read_b128 v[248:251], v207 offset:47104
	s_cmp_lg_u32 s7, 16
	s_mov_b32 s5, s8
	s_mov_b32 s6, s7
	s_cbranch_scc1 .LBB0_768
	s_waitcnt vmcnt(0) lgkmcnt(0)
	v_mov_b32_e32 v170, 0x358637bd
	v_mov_b32_e32 v194, 0x25a08
	v_mbcnt_lo_u32_b32 v195, -1, 0
	v_mbcnt_hi_u32_b32 v196, -1, v195
	v_mov_b32_e32 v197, 0x24000
	v_mov_b32_e32 v198, 0x1fa0
	v_mov_b32_e32 v199, 0x41b17218
	v_mov_b32_e32 v200, 0x7e800
	v_mov_b32_e32 v201, 0xfd0
	v_mov_b32_e32 v202, 0x100
	v_mov_b32_e32 v203, 0x200
	v_mov_b32_e32 v204, 0x7f61b1e6
	v_mov_b32_e32 v205, 0xff800000
	v_mov_b32_e32 v206, 0x3f80
	v_mov_b32_e32 v207, 0x1d400
	v_mov_b32_e32 v0, v171
	s_waitcnt vmcnt(7)
	v_mov_b32_e32 v110, v171
	s_barrier
	v_max_f32_e32 v113, v159, v159
	v_ashrrev_i32_e32 v111, 1, v110
	v_and_b32_e32 v111, 0xffffffc0, v111
	v_add_u32_e32 v111, s1, v111
	s_waitcnt vmcnt(6)
	v_and_or_b32 v118, v0, 15, v111
	v_lshlrev_b32_e32 v110, 1, v110
	v_lshrrev_b32_e32 v0, 2, v0
	v_and_b32_e32 v110, 0x80, v110
	v_and_b32_e32 v0, 12, v0
	v_or3_b32 v112, v0, v110, s0
	v_max_f32_e32 v0, v158, v158
	v_max_f32_e32 v113, 0, v113
	s_waitcnt vmcnt(5)
	v_max_f32_e32 v116, v160, v160
	v_max_f32_e32 v117, v161, v161
	v_mov_b64_e32 v[110:111], s[78:79]
	v_max_f32_e32 v0, 0, v0
	v_max_f32_e32 v116, 0, v116
	v_max_f32_e32 v117, 0, v117
	v_mul_f32_e32 v119, v113, v113
	v_ashrrev_i32_e32 v113, 31, v112
	v_mad_i64_i32 v[114:115], s[0:1], v118, s10, v[110:111]
	v_mul_f32_e32 v0, v0, v0
	v_mul_f32_e32 v116, v116, v116
	v_mul_f32_e32 v117, v117, v117
	v_lshlrev_b64 v[112:113], 1, v[112:113]
	v_lshl_add_u64 v[114:115], v[114:115], 0, v[112:113]
	v_cvt_pk_bf16_f32 v117, v116, v117
	v_cvt_pk_bf16_f32 v116, v0, v119
	global_store_dwordx2 v[114:115], v[116:117], off
	v_max_f32_e32 v0, v154, v154
	v_max_f32_e32 v116, v155, v155
	v_max_f32_e32 v117, v156, v156
	v_max_f32_e32 v119, v157, v157
	v_max_f32_e32 v0, 0, v0
	v_max_f32_e32 v116, 0, v116
	v_max_f32_e32 v117, 0, v117
	v_max_f32_e32 v119, 0, v119
	v_mul_f32_e32 v0, v0, v0
	v_mul_f32_e32 v116, v116, v116
	v_mul_f32_e32 v117, v117, v117
	v_mul_f32_e32 v119, v119, v119
	v_cvt_pk_bf16_f32 v117, v117, v119
	v_cvt_pk_bf16_f32 v116, v0, v116
	global_store_dwordx2 v[114:115], v[116:117], off offset:32
	v_max_f32_e32 v0, v146, v146
	v_max_f32_e32 v116, v147, v147
	v_max_f32_e32 v117, v148, v148
	v_max_f32_e32 v119, v149, v149
	v_max_f32_e32 v0, 0, v0
	v_max_f32_e32 v116, 0, v116
	v_max_f32_e32 v117, 0, v117
	v_max_f32_e32 v119, 0, v119
	v_mul_f32_e32 v0, v0, v0
	v_mul_f32_e32 v116, v116, v116
	v_mul_f32_e32 v117, v117, v117
	v_mul_f32_e32 v119, v119, v119
	v_cvt_pk_bf16_f32 v117, v117, v119
	v_cvt_pk_bf16_f32 v116, v0, v116
	global_store_dwordx2 v[114:115], v[116:117], off offset:64
	v_max_f32_e32 v0, v142, v142
	v_max_f32_e32 v116, v143, v143
	v_max_f32_e32 v117, v144, v144
	v_max_f32_e32 v119, v145, v145
;   __device__ __forceinline__ u16* P() const { return (u16*)(ws + O_P); }
; #define EPI_LOOP(MT_, NT_)                                                \
;   const int l_ = ltid() & 63, w_ = ltid() >> 6;                           \
;   const int wm_ = w_ >> 1, wn_ = w_ & 1, fr_ = l_ & 15, fq_ = l_ >> 4;    \
;   _Pragma("unroll") for (int mi = 0; mi < MT_; ++mi)                      \
;   _Pragma("unroll") for (int ni = 0; ni < NT_; ++ni)
; DI void phase_ff1(const Params& p, int l, char* smem) {
;     ...
;     EPI_LOOP(4, 8) {
;       const int row = r0 + wm_ * 64 + mi * 16 + fr_, col = c0 + wn_ * 128 + ni * 16 + fq_ * 4;
;       float a0 = fmaxf(acc[mi][ni][0], 0.f), a1 = fmaxf(acc[mi][ni][1], 0.f), a2 = fmaxf(acc[mi][ni][2], 0.f), a3 = fmaxf(acc[mi][ni][3], 0.f);
;       uint2 o;
;       o.x = pack2(a0 * a0, a1 * a1); o.y = pack2(a2 * a2, a3 * a3);
;       *(uint2*)(p.P() + (size_t)row * LDH + col) = o;
	v_max_f32_e32 v0, 0, v0
	v_max_f32_e32 v116, 0, v116
	v_max_f32_e32 v117, 0, v117
	v_max_f32_e32 v119, 0, v119
	v_mul_f32_e32 v0, v0, v0
	v_mul_f32_e32 v116, v116, v116
	v_mul_f32_e32 v117, v117, v117
	v_mul_f32_e32 v119, v119, v119
	v_cvt_pk_bf16_f32 v117, v117, v119
	v_cvt_pk_bf16_f32 v116, v0, v116
	global_store_dwordx2 v[114:115], v[116:117], off offset:96
	v_max_f32_e32 v0, v138, v138
	v_max_f32_e32 v116, v139, v139
	v_max_f32_e32 v0, 0, v0
	v_max_f32_e32 v116, 0, v116
	v_mul_f32_e32 v0, v0, v0
	v_mul_f32_e32 v116, v116, v116
	v_cvt_pk_bf16_f32 v116, v0, v116
	v_max_f32_e32 v0, v106, v106
	v_max_f32_e32 v106, v107, v107
	v_max_f32_e32 v0, 0, v0
	v_max_f32_e32 v106, 0, v106
	v_mul_f32_e32 v0, v0, v0
	v_mul_f32_e32 v106, v106, v106
	v_cvt_pk_bf16_f32 v106, v0, v106
	v_max_f32_e32 v0, v102, v102
	v_max_f32_e32 v102, v103, v103
	v_max_f32_e32 v0, 0, v0
	v_max_f32_e32 v102, 0, v102
	v_mul_f32_e32 v0, v0, v0
	v_mul_f32_e32 v102, v102, v102
	v_cvt_pk_bf16_f32 v102, v0, v102
	v_max_f32_e32 v0, v98, v98
	v_max_f32_e32 v98, v99, v99
	v_max_f32_e32 v99, v100, v100
	v_max_f32_e32 v100, v101, v101
	v_max_f32_e32 v0, 0, v0
	v_max_f32_e32 v98, 0, v98
	v_max_f32_e32 v99, 0, v99
	v_max_f32_e32 v100, 0, v100
	v_mul_f32_e32 v0, v0, v0
	v_mul_f32_e32 v98, v98, v98
	v_mul_f32_e32 v99, v99, v99
	v_mul_f32_e32 v100, v100, v100
	v_cvt_pk_bf16_f32 v99, v99, v100
	v_cvt_pk_bf16_f32 v98, v0, v98
	v_or_b32_e32 v0, 16, v118
	global_store_dwordx2 v[114:115], v[98:99], off offset:224
	v_mad_i64_i32 v[98:99], s[0:1], v0, s10, v[110:111]
	v_max_f32_e32 v0, v94, v94
	v_max_f32_e32 v94, v95, v95
	v_max_f32_e32 v95, v96, v96
	v_max_f32_e32 v96, v97, v97
	v_max_f32_e32 v0, 0, v0
	v_max_f32_e32 v94, 0, v94
	v_max_f32_e32 v95, 0, v95
	v_max_f32_e32 v96, 0, v96
	v_mul_f32_e32 v0, v0, v0
	v_mul_f32_e32 v100, v94, v94
	v_mul_f32_e32 v97, v95, v95
	v_mul_f32_e32 v96, v96, v96
	v_cvt_pk_bf16_f32 v97, v97, v96
	v_cvt_pk_bf16_f32 v96, v0, v100
	v_max_f32_e32 v0, v90, v90
	v_max_f32_e32 v90, v91, v91
	v_max_f32_e32 v0, 0, v0
	v_max_f32_e32 v90, 0, v90
	v_mul_f32_e32 v0, v0, v0
	v_mul_f32_e32 v90, v90, v90
	v_cvt_pk_bf16_f32 v90, v0, v90
	v_max_f32_e32 v0, v86, v86
	v_max_f32_e32 v86, v87, v87
	v_max_f32_e32 v0, 0, v0
	v_max_f32_e32 v86, 0, v86
	v_mul_f32_e32 v0, v0, v0
	v_mul_f32_e32 v86, v86, v86
	v_cvt_pk_bf16_f32 v86, v0, v86
	v_max_f32_e32 v0, v82, v82
	v_max_f32_e32 v82, v83, v83
	v_max_f32_e32 v0, 0, v0
	v_max_f32_e32 v82, 0, v82
	v_mul_f32_e32 v0, v0, v0
	v_mul_f32_e32 v82, v82, v82
	v_cvt_pk_bf16_f32 v82, v0, v82
	v_max_f32_e32 v0, v78, v78
	v_max_f32_e32 v78, v79, v79
	v_max_f32_e32 v0, 0, v0
	v_max_f32_e32 v78, 0, v78
	v_mul_f32_e32 v0, v0, v0
	v_mul_f32_e32 v78, v78, v78
	v_cvt_pk_bf16_f32 v78, v0, v78
	v_max_f32_e32 v0, v74, v74
	v_max_f32_e32 v74, v75, v75
	v_max_f32_e32 v0, 0, v0
	v_max_f32_e32 v74, 0, v74
	v_mul_f32_e32 v0, v0, v0
	v_mul_f32_e32 v74, v74, v74
	v_cvt_pk_bf16_f32 v74, v0, v74
	v_max_f32_e32 v0, v70, v70
	v_max_f32_e32 v70, v71, v71
	v_max_f32_e32 v0, 0, v0
	v_max_f32_e32 v70, 0, v70
	v_mul_f32_e32 v0, v0, v0
	v_mul_f32_e32 v70, v70, v70
	v_cvt_pk_bf16_f32 v70, v0, v70
	v_max_f32_e32 v0, v66, v66
	v_max_f32_e32 v66, v67, v67
	v_max_f32_e32 v67, v68, v68
	v_max_f32_e32 v68, v69, v69
	v_max_f32_e32 v0, 0, v0
	v_max_f32_e32 v66, 0, v66
	v_max_f32_e32 v67, 0, v67
	v_max_f32_e32 v68, 0, v68
	v_mul_f32_e32 v0, v0, v0
	v_mul_f32_e32 v66, v66, v66
	v_mul_f32_e32 v67, v67, v67
	v_mul_f32_e32 v68, v68, v68
	v_lshl_add_u64 v[94:95], v[98:99], 0, v[112:113]
	v_cvt_pk_bf16_f32 v67, v67, v68
	v_cvt_pk_bf16_f32 v66, v0, v66
	v_or_b32_e32 v0, 32, v118
	global_store_dwordx2 v[94:95], v[66:67], off offset:224
	v_mad_i64_i32 v[66:67], s[0:1], v0, s10, v[110:111]
	v_max_f32_e32 v0, v62, v62
	v_max_f32_e32 v62, v63, v63
	v_max_f32_e32 v63, v64, v64
	v_max_f32_e32 v64, v65, v65
	v_max_f32_e32 v0, 0, v0
	v_max_f32_e32 v62, 0, v62
	v_max_f32_e32 v63, 0, v63
	v_max_f32_e32 v64, 0, v64
	v_mul_f32_e32 v0, v0, v0
	v_mul_f32_e32 v68, v62, v62
	v_mul_f32_e32 v65, v63, v63
	v_mul_f32_e32 v64, v64, v64
	v_cvt_pk_bf16_f32 v65, v65, v64
	v_cvt_pk_bf16_f32 v64, v0, v68
	v_max_f32_e32 v0, v58, v58
	v_max_f32_e32 v58, v59, v59
	v_max_f32_e32 v0, 0, v0
	v_max_f32_e32 v58, 0, v58
	v_mul_f32_e32 v0, v0, v0
	v_mul_f32_e32 v58, v58, v58
	v_cvt_pk_bf16_f32 v58, v0, v58
	v_max_f32_e32 v0, v54, v54
	v_max_f32_e32 v54, v55, v55
	v_max_f32_e32 v0, 0, v0
	v_max_f32_e32 v54, 0, v54
	v_mul_f32_e32 v0, v0, v0
	v_mul_f32_e32 v54, v54, v54
	v_cvt_pk_bf16_f32 v54, v0, v54
	v_max_f32_e32 v0, v50, v50
	v_max_f32_e32 v50, v51, v51
	v_max_f32_e32 v0, 0, v0
	v_max_f32_e32 v50, 0, v50
	v_mul_f32_e32 v0, v0, v0
	v_mul_f32_e32 v50, v50, v50
	v_cvt_pk_bf16_f32 v50, v0, v50
	v_max_f32_e32 v0, v46, v46
	v_max_f32_e32 v46, v47, v47
	v_max_f32_e32 v0, 0, v0
	v_max_f32_e32 v46, 0, v46
	v_mul_f32_e32 v0, v0, v0
	v_mul_f32_e32 v46, v46, v46
	v_cvt_pk_bf16_f32 v46, v0, v46
	v_max_f32_e32 v0, v42, v42
	v_max_f32_e32 v42, v43, v43
	v_max_f32_e32 v0, 0, v0
	v_max_f32_e32 v42, 0, v42
	v_mul_f32_e32 v0, v0, v0
	v_mul_f32_e32 v42, v42, v42
	v_cvt_pk_bf16_f32 v42, v0, v42
	v_max_f32_e32 v0, v38, v38
	v_max_f32_e32 v38, v39, v39
	v_max_f32_e32 v0, 0, v0
	v_max_f32_e32 v38, 0, v38
	v_mul_f32_e32 v0, v0, v0
	v_mul_f32_e32 v38, v38, v38
	v_cvt_pk_bf16_f32 v38, v0, v38
	v_max_f32_e32 v0, v34, v34
	v_max_f32_e32 v34, v35, v35
	v_max_f32_e32 v35, v36, v36
	v_max_f32_e32 v36, v37, v37
	v_max_f32_e32 v0, 0, v0
	v_max_f32_e32 v34, 0, v34
	v_max_f32_e32 v35, 0, v35
	v_max_f32_e32 v36, 0, v36
	v_mul_f32_e32 v0, v0, v0
	v_mul_f32_e32 v34, v34, v34
	v_mul_f32_e32 v35, v35, v35
	v_mul_f32_e32 v36, v36, v36
	v_lshl_add_u64 v[62:63], v[66:67], 0, v[112:113]
;   __device__ __forceinline__ u16* P() const { return (u16*)(ws + O_P); }
; #define EPI_LOOP(MT_, NT_)                                                \
;   const int l_ = ltid() & 63, w_ = ltid() >> 6;                           \
;   const int wm_ = w_ >> 1, wn_ = w_ & 1, fr_ = l_ & 15, fq_ = l_ >> 4;    \
;   _Pragma("unroll") for (int mi = 0; mi < MT_; ++mi)                      \
;   _Pragma("unroll") for (int ni = 0; ni < NT_; ++ni)
; DI void phase_ff1(const Params& p, int l, char* smem) {
;     ...
;     EPI_LOOP(4, 8) {
;       const int row = r0 + wm_ * 64 + mi * 16 + fr_, col = c0 + wn_ * 128 + ni * 16 + fq_ * 4;
;       float a0 = fmaxf(acc[mi][ni][0], 0.f), a1 = fmaxf(acc[mi][ni][1], 0.f), a2 = fmaxf(acc[mi][ni][2], 0.f), a3 = fmaxf(acc[mi][ni][3], 0.f);
;       uint2 o;
;       o.x = pack2(a0 * a0, a1 * a1); o.y = pack2(a2 * a2, a3 * a3);
;       *(uint2*)(p.P() + (size_t)row * LDH + col) = o;
	v_cvt_pk_bf16_f32 v35, v35, v36
	v_cvt_pk_bf16_f32 v34, v0, v34
	v_or_b32_e32 v0, 48, v118
	global_store_dwordx2 v[62:63], v[34:35], off offset:224
	v_mad_i64_i32 v[34:35], s[0:1], v0, s10, v[110:111]
	v_max_f32_e32 v0, v30, v30
	v_max_f32_e32 v30, v31, v31
	v_max_f32_e32 v31, v32, v32
	v_max_f32_e32 v32, v33, v33
	v_max_f32_e32 v0, 0, v0
	v_max_f32_e32 v30, 0, v30
	v_max_f32_e32 v31, 0, v31
	v_max_f32_e32 v32, 0, v32
	v_mul_f32_e32 v0, v0, v0
	v_mul_f32_e32 v36, v30, v30
	v_mul_f32_e32 v33, v31, v31
	v_mul_f32_e32 v32, v32, v32
	v_cvt_pk_bf16_f32 v33, v33, v32
	v_cvt_pk_bf16_f32 v32, v0, v36
	v_max_f32_e32 v0, v26, v26
	v_max_f32_e32 v26, v27, v27
	v_max_f32_e32 v0, 0, v0
	v_max_f32_e32 v26, 0, v26
	v_mul_f32_e32 v0, v0, v0
	v_mul_f32_e32 v26, v26, v26
	v_cvt_pk_bf16_f32 v26, v0, v26
	v_max_f32_e32 v0, v22, v22
	v_max_f32_e32 v22, v23, v23
	v_max_f32_e32 v0, 0, v0
	v_max_f32_e32 v22, 0, v22
	v_mul_f32_e32 v0, v0, v0
	v_mul_f32_e32 v22, v22, v22
	v_cvt_pk_bf16_f32 v22, v0, v22
	v_max_f32_e32 v0, v18, v18
	v_max_f32_e32 v18, v19, v19
	v_max_f32_e32 v0, 0, v0
	v_max_f32_e32 v18, 0, v18
	v_mul_f32_e32 v0, v0, v0
	v_mul_f32_e32 v18, v18, v18
	v_cvt_pk_bf16_f32 v18, v0, v18
	v_max_f32_e32 v0, v14, v14
	v_max_f32_e32 v14, v15, v15
	v_max_f32_e32 v0, 0, v0
	v_max_f32_e32 v14, 0, v14
	v_mul_f32_e32 v0, v0, v0
	v_mul_f32_e32 v14, v14, v14
	v_cvt_pk_bf16_f32 v14, v0, v14
	v_max_f32_e32 v0, v10, v10
	v_max_f32_e32 v10, v11, v11
	v_max_f32_e32 v0, 0, v0
	v_max_f32_e32 v10, 0, v10
	v_mul_f32_e32 v0, v0, v0
	v_mul_f32_e32 v10, v10, v10
	v_cvt_pk_bf16_f32 v10, v0, v10
	v_max_f32_e32 v0, v6, v6
	v_max_f32_e32 v6, v7, v7
	v_max_f32_e32 v0, 0, v0
	v_max_f32_e32 v6, 0, v6
	v_mul_f32_e32 v0, v0, v0
	v_mul_f32_e32 v6, v6, v6
	v_max_f32_e32 v117, v140, v140
	v_max_f32_e32 v119, v141, v141
	v_max_f32_e32 v107, v108, v108
	v_max_f32_e32 v108, v109, v109
	v_max_f32_e32 v103, v104, v104
	v_max_f32_e32 v104, v105, v105
	v_max_f32_e32 v91, v92, v92
	v_max_f32_e32 v92, v93, v93
	v_max_f32_e32 v87, v88, v88
	v_max_f32_e32 v88, v89, v89
	v_max_f32_e32 v83, v84, v84
	v_max_f32_e32 v84, v85, v85
	v_max_f32_e32 v79, v80, v80
	v_max_f32_e32 v80, v81, v81
	v_max_f32_e32 v75, v76, v76
	v_max_f32_e32 v76, v77, v77
	v_max_f32_e32 v71, v72, v72
	v_max_f32_e32 v72, v73, v73
	v_max_f32_e32 v59, v60, v60
	v_max_f32_e32 v60, v61, v61
	v_max_f32_e32 v55, v56, v56
	v_max_f32_e32 v56, v57, v57
	v_max_f32_e32 v51, v52, v52
	v_max_f32_e32 v52, v53, v53
	v_max_f32_e32 v47, v48, v48
	v_max_f32_e32 v48, v49, v49
	v_max_f32_e32 v43, v44, v44
	v_max_f32_e32 v44, v45, v45
	v_max_f32_e32 v39, v40, v40
	v_max_f32_e32 v40, v41, v41
	v_max_f32_e32 v27, v28, v28
	v_max_f32_e32 v28, v29, v29
	v_max_f32_e32 v23, v24, v24
	v_max_f32_e32 v24, v25, v25
	v_max_f32_e32 v19, v20, v20
	v_max_f32_e32 v20, v21, v21
	v_max_f32_e32 v15, v16, v16
	v_max_f32_e32 v16, v17, v17
	v_max_f32_e32 v11, v12, v12
	v_max_f32_e32 v12, v13, v13
	v_max_f32_e32 v7, v8, v8
	v_max_f32_e32 v8, v9, v9
	v_cvt_pk_bf16_f32 v6, v0, v6
	v_max_f32_e32 v0, v2, v2
	v_max_f32_e32 v2, v3, v3
	v_max_f32_e32 v3, v4, v4
	v_max_f32_e32 v4, v5, v5
	v_max_f32_e32 v117, 0, v117
	v_max_f32_e32 v119, 0, v119
	v_max_f32_e32 v107, 0, v107
	v_max_f32_e32 v108, 0, v108
	v_max_f32_e32 v103, 0, v103
	v_max_f32_e32 v104, 0, v104
	v_max_f32_e32 v91, 0, v91
	v_max_f32_e32 v92, 0, v92
	v_max_f32_e32 v87, 0, v87
	v_max_f32_e32 v88, 0, v88
	v_max_f32_e32 v83, 0, v83
	v_max_f32_e32 v84, 0, v84
	v_max_f32_e32 v79, 0, v79
	v_max_f32_e32 v80, 0, v80
	v_max_f32_e32 v75, 0, v75
	v_max_f32_e32 v76, 0, v76
	v_max_f32_e32 v71, 0, v71
	v_max_f32_e32 v72, 0, v72
	v_max_f32_e32 v59, 0, v59
	v_max_f32_e32 v60, 0, v60
	v_max_f32_e32 v55, 0, v55
	v_max_f32_e32 v56, 0, v56
	v_max_f32_e32 v51, 0, v51
	v_max_f32_e32 v52, 0, v52
	v_max_f32_e32 v47, 0, v47
	v_max_f32_e32 v48, 0, v48
	v_max_f32_e32 v43, 0, v43
	v_max_f32_e32 v44, 0, v44
	v_max_f32_e32 v39, 0, v39
	v_max_f32_e32 v40, 0, v40
	v_max_f32_e32 v27, 0, v27
	v_max_f32_e32 v28, 0, v28
;   __device__ __forceinline__ u16* P() const { return (u16*)(ws + O_P); }
; #define EPI_LOOP(MT_, NT_)                                                \
;   const int l_ = ltid() & 63, w_ = ltid() >> 6;                           \
;   const int wm_ = w_ >> 1, wn_ = w_ & 1, fr_ = l_ & 15, fq_ = l_ >> 4;    \
;   _Pragma("unroll") for (int mi = 0; mi < MT_; ++mi)                      \
;   _Pragma("unroll") for (int ni = 0; ni < NT_; ++ni)
; DI void phase_ff1(const Params& p, int l, char* smem) {
;     ...
;     EPI_LOOP(4, 8) {
;       const int row = r0 + wm_ * 64 + mi * 16 + fr_, col = c0 + wn_ * 128 + ni * 16 + fq_ * 4;
;       float a0 = fmaxf(acc[mi][ni][0], 0.f), a1 = fmaxf(acc[mi][ni][1], 0.f), a2 = fmaxf(acc[mi][ni][2], 0.f), a3 = fmaxf(acc[mi][ni][3], 0.f);
;       uint2 o;
;       o.x = pack2(a0 * a0, a1 * a1); o.y = pack2(a2 * a2, a3 * a3);
;       *(uint2*)(p.P() + (size_t)row * LDH + col) = o;
	v_max_f32_e32 v23, 0, v23
	v_max_f32_e32 v24, 0, v24
	v_max_f32_e32 v19, 0, v19
	v_max_f32_e32 v20, 0, v20
	v_max_f32_e32 v15, 0, v15
	v_max_f32_e32 v16, 0, v16
	v_max_f32_e32 v11, 0, v11
	v_max_f32_e32 v12, 0, v12
	v_max_f32_e32 v7, 0, v7
	v_max_f32_e32 v8, 0, v8
	v_max_f32_e32 v0, 0, v0
	v_max_f32_e32 v2, 0, v2
	v_max_f32_e32 v3, 0, v3
	v_max_f32_e32 v4, 0, v4
	v_mul_f32_e32 v117, v117, v117
	v_mul_f32_e32 v119, v119, v119
	v_mul_f32_e32 v107, v107, v107
	v_mul_f32_e32 v108, v108, v108
	v_mul_f32_e32 v103, v103, v103
	v_mul_f32_e32 v104, v104, v104
	v_mul_f32_e32 v91, v91, v91
	v_mul_f32_e32 v92, v92, v92
	v_mul_f32_e32 v87, v87, v87
	v_mul_f32_e32 v88, v88, v88
	v_mul_f32_e32 v83, v83, v83
	v_mul_f32_e32 v84, v84, v84
	v_mul_f32_e32 v79, v79, v79
	v_mul_f32_e32 v80, v80, v80
	v_mul_f32_e32 v75, v75, v75
	v_mul_f32_e32 v76, v76, v76
	v_mul_f32_e32 v71, v71, v71
	v_mul_f32_e32 v72, v72, v72
	v_mul_f32_e32 v59, v59, v59
	v_mul_f32_e32 v60, v60, v60
	v_mul_f32_e32 v55, v55, v55
	v_mul_f32_e32 v56, v56, v56
	v_mul_f32_e32 v51, v51, v51
	v_mul_f32_e32 v52, v52, v52
	v_mul_f32_e32 v47, v47, v47
	v_mul_f32_e32 v48, v48, v48
	v_mul_f32_e32 v43, v43, v43
	v_mul_f32_e32 v44, v44, v44
	v_mul_f32_e32 v39, v39, v39
	v_mul_f32_e32 v40, v40, v40
	v_mul_f32_e32 v27, v27, v27
	v_mul_f32_e32 v28, v28, v28
	v_mul_f32_e32 v23, v23, v23
	v_mul_f32_e32 v24, v24, v24
	v_mul_f32_e32 v19, v19, v19
	v_mul_f32_e32 v20, v20, v20
	v_mul_f32_e32 v15, v15, v15
	v_mul_f32_e32 v16, v16, v16
	v_mul_f32_e32 v11, v11, v11
	v_mul_f32_e32 v12, v12, v12
	v_mul_f32_e32 v7, v7, v7
	v_mul_f32_e32 v8, v8, v8
	v_mul_f32_e32 v0, v0, v0
	v_mul_f32_e32 v2, v2, v2
	v_mul_f32_e32 v3, v3, v3
	v_mul_f32_e32 v4, v4, v4
	v_cvt_pk_bf16_f32 v117, v117, v119
	v_cvt_pk_bf16_f32 v107, v107, v108
	v_cvt_pk_bf16_f32 v103, v103, v104
	v_cvt_pk_bf16_f32 v91, v91, v92
	v_cvt_pk_bf16_f32 v87, v87, v88
	v_cvt_pk_bf16_f32 v83, v83, v84
	v_cvt_pk_bf16_f32 v79, v79, v80
	v_cvt_pk_bf16_f32 v75, v75, v76
	v_cvt_pk_bf16_f32 v71, v71, v72
	v_cvt_pk_bf16_f32 v59, v59, v60
	v_cvt_pk_bf16_f32 v55, v55, v56
	v_cvt_pk_bf16_f32 v51, v51, v52
	v_cvt_pk_bf16_f32 v47, v47, v48
	v_cvt_pk_bf16_f32 v43, v43, v44
	v_cvt_pk_bf16_f32 v39, v39, v40
	v_lshl_add_u64 v[30:31], v[34:35], 0, v[112:113]
	v_cvt_pk_bf16_f32 v27, v27, v28
	v_cvt_pk_bf16_f32 v23, v23, v24
	v_cvt_pk_bf16_f32 v19, v19, v20
	v_cvt_pk_bf16_f32 v15, v15, v16
	v_cvt_pk_bf16_f32 v11, v11, v12
	v_cvt_pk_bf16_f32 v7, v7, v8
	v_cvt_pk_bf16_f32 v3, v3, v4
	v_cvt_pk_bf16_f32 v2, v0, v2
	s_add_i32 s4, s4, 1
	s_mov_b64 s[0:1], 0
	global_store_dwordx2 v[114:115], v[116:117], off offset:128
	global_store_dwordx2 v[114:115], v[106:107], off offset:160
	global_store_dwordx2 v[114:115], v[102:103], off offset:192
	global_store_dwordx2 v[94:95], v[96:97], off
	global_store_dwordx2 v[94:95], v[90:91], off offset:32
	global_store_dwordx2 v[94:95], v[86:87], off offset:64
	global_store_dwordx2 v[94:95], v[82:83], off offset:96
	global_store_dwordx2 v[94:95], v[78:79], off offset:128
	global_store_dwordx2 v[94:95], v[74:75], off offset:160
	global_store_dwordx2 v[94:95], v[70:71], off offset:192
	global_store_dwordx2 v[62:63], v[64:65], off
	global_store_dwordx2 v[62:63], v[58:59], off offset:32
	global_store_dwordx2 v[62:63], v[54:55], off offset:64
	global_store_dwordx2 v[62:63], v[50:51], off offset:96
	global_store_dwordx2 v[62:63], v[46:47], off offset:128
	global_store_dwordx2 v[62:63], v[42:43], off offset:160
	global_store_dwordx2 v[62:63], v[38:39], off offset:192
	global_store_dwordx2 v[30:31], v[32:33], off
	global_store_dwordx2 v[30:31], v[26:27], off offset:32
	global_store_dwordx2 v[30:31], v[22:23], off offset:64
	global_store_dwordx2 v[30:31], v[18:19], off offset:96
	global_store_dwordx2 v[30:31], v[14:15], off offset:128
	global_store_dwordx2 v[30:31], v[10:11], off offset:160
	global_store_dwordx2 v[30:31], v[6:7], off offset:192
	global_store_dwordx2 v[30:31], v[2:3], off offset:224
	s_branch .LBB0_765

; DI f32x4 mfma16(bf16x8 a, bf16x8 b, f32x4 c) { return __builtin_amdgcn_mfma_f32_16x16x32_bf16(a, b, c, 0, 0, 0); }
; #define GLOAD(kt) { GL1(0, kt) GL1(1, kt) GL1(2, kt) GL1(3, kt) }
; #define SSTORE(buf)                              \
;   {                                              \
;     char* as_ = smem + (buf) * BUF;              \
;     char* bs_ = as_ + ASZ;                       \
;     SS1(0) SS1(1) SS1(2) SS1(3)                  \
;   }
; template <int MT, int NT>
; DI void gemm_core(const u16* __restrict__ A, int lda, const u16* __restrict__ B, int ldb, int K,
;                   f32x4 (&acc)[MT][NT], char* smem) {
;     ...
;   for (int kt = 0; kt < nk; ++kt) {
;     __syncthreads();
;     SSTORE((kt + 1) & 1);
;     { const int kn_ = (kt + 2 < nk) ? kt + 2 : nk - 1; GLOAD(kn_); }
;     const char* as = smem + (kt & 1) * BUF;
;     const char* bs = as + ASZ;
; #pragma unroll
;     for (int kk = 0; kk < 2; ++kk) {
;       bf16x8 xf[MT], wf[NT];
; #pragma unroll
;       for (int mi = 0; mi < MT; ++mi)
;         xf[mi] = *(const bf16x8*)(as + (wm * (MT * 16) + mi * 16 + fr) * 128 + (((kk * 4 + fq) ^ fsw) * 16));
; #pragma unroll
;       for (int ni = 0; ni < NT; ++ni)
;         wf[ni] = *(const bf16x8*)(bs + (wn * (NT * 16) + ni * 16 + fr) * 128 + (((kk * 4 + fq) ^ fsw) * 16));
;       __builtin_amdgcn_s_setprio(1);
; #pragma unroll
;       for (int mi = 0; mi < MT; ++mi)
; #pragma unroll
;         for (int ni = 0; ni < NT; ++ni) acc[mi][ni] = mfma16(wf[ni], xf[mi], acc[mi][ni]);
;       __builtin_amdgcn_s_setprio(0);
;     }
.LBB0_797:
	s_add_i32 s8, s5, 0x10000
	s_and_b32 s9, s8, 0x10000
	s_add_i32 s7, s6, 1
	s_min_u32 s6, s6, 61
	s_lshl_b32 s54, s6, 7
	s_and_b32 s5, s5, 0x10000
	v_or_b32_e32 v206, s5, v189
	v_add_u32_e32 v207, v206, v188
	v_add_u32_e32 v206, v206, v187
	v_add3_u32 v170, s9, v0, v173
	s_waitcnt lgkmcnt(10)
	v_mfma_f32_16x16x32_bf16 v[158:161], v[220:223], v[190:193], v[158:161]
	s_waitcnt vmcnt(0)
	ds_write_b128 v170, v[114:117]
	s_waitcnt lgkmcnt(10)
	v_mfma_f32_16x16x32_bf16 v[94:97], v[220:223], v[208:211], v[94:97]
	v_lshl_add_u64 v[114:115], v[162:163], 0, s[54:55]
	global_load_dwordx4 v[114:117], v[114:115], off offset:256
	s_waitcnt lgkmcnt(8)
	v_mfma_f32_16x16x32_bf16 v[62:65], v[220:223], v[212:215], v[62:65]
	ds_write_b128 v170, v[122:125] offset:32768
	s_waitcnt lgkmcnt(3)
	v_mfma_f32_16x16x32_bf16 v[30:33], v[220:223], v[216:219], v[30:33]
	v_lshl_add_u64 v[122:123], v[164:165], 0, s[54:55]
	global_load_dwordx4 v[122:125], v[122:123], off offset:256
	ds_read_b128 v[194:197], v206
	v_mfma_f32_16x16x32_bf16 v[150:153], v[224:227], v[190:193], v[150:153]
	ds_read_b128 v[220:223], v207 offset:32768
	ds_write_b128 v170, v[118:121] offset:8192
	v_mfma_f32_16x16x32_bf16 v[90:93], v[224:227], v[208:211], v[90:93]
	v_lshl_add_u64 v[118:119], v[166:167], 0, s[54:55]
	global_load_dwordx4 v[118:121], v[118:119], off offset:256
	v_mfma_f32_16x16x32_bf16 v[58:61], v[224:227], v[212:215], v[58:61]
	v_mfma_f32_16x16x32_bf16 v[26:29], v[224:227], v[216:219], v[26:29]
	ds_read_b128 v[198:201], v206 offset:2048
	v_mfma_f32_16x16x32_bf16 v[146:149], v[228:231], v[190:193], v[146:149]
	ds_read_b128 v[224:227], v207 offset:34816
	ds_write_b128 v170, v[134:137] offset:40960
	v_mfma_f32_16x16x32_bf16 v[86:89], v[228:231], v[208:211], v[86:89]
	v_lshl_add_u64 v[134:135], v[168:169], 0, s[54:55]
	global_load_dwordx4 v[134:137], v[134:135], off offset:256
	v_mfma_f32_16x16x32_bf16 v[54:57], v[228:231], v[212:215], v[54:57]
	v_mfma_f32_16x16x32_bf16 v[22:25], v[228:231], v[216:219], v[22:25]
	ds_read_b128 v[202:205], v206 offset:4096
	v_mfma_f32_16x16x32_bf16 v[126:129], v[232:235], v[190:193], v[126:129]
	ds_read_b128 v[228:231], v207 offset:36864
	ds_write_b128 v170, v[130:133] offset:16384
	v_mfma_f32_16x16x32_bf16 v[82:85], v[232:235], v[208:211], v[82:85]
	v_lshl_add_u64 v[130:131], v[176:177], 0, s[54:55]
	global_load_dwordx4 v[130:133], v[130:131], off offset:256
	v_mfma_f32_16x16x32_bf16 v[50:53], v[232:235], v[212:215], v[50:53]
	v_mfma_f32_16x16x32_bf16 v[18:21], v[232:235], v[216:219], v[18:21]
	v_mfma_f32_16x16x32_bf16 v[110:113], v[236:239], v[190:193], v[110:113]
	ds_read_b128 v[232:235], v207 offset:38912
	ds_write_b128 v170, v[142:145] offset:49152
	v_mfma_f32_16x16x32_bf16 v[78:81], v[236:239], v[208:211], v[78:81]
	v_lshl_add_u64 v[142:143], v[178:179], 0, s[54:55]
	global_load_dwordx4 v[142:145], v[142:143], off offset:256
	v_mfma_f32_16x16x32_bf16 v[46:49], v[236:239], v[212:215], v[46:49]
	v_mfma_f32_16x16x32_bf16 v[14:17], v[236:239], v[216:219], v[14:17]
	v_mfma_f32_16x16x32_bf16 v[106:109], v[240:243], v[190:193], v[106:109]
	ds_read_b128 v[236:239], v207 offset:40960
	ds_write_b128 v170, v[138:141] offset:24576
	v_mfma_f32_16x16x32_bf16 v[74:77], v[240:243], v[208:211], v[74:77]
	v_lshl_add_u64 v[138:139], v[180:181], 0, s[54:55]
	global_load_dwordx4 v[138:141], v[138:139], off offset:256
	v_mfma_f32_16x16x32_bf16 v[42:45], v[240:243], v[212:215], v[42:45]
	v_mfma_f32_16x16x32_bf16 v[10:13], v[240:243], v[216:219], v[10:13]
	v_mfma_f32_16x16x32_bf16 v[102:105], v[244:247], v[190:193], v[102:105]
	ds_read_b128 v[240:243], v207 offset:43008
	ds_write_b128 v170, v[154:157] offset:57344
	v_mfma_f32_16x16x32_bf16 v[70:73], v[244:247], v[208:211], v[70:73]
	v_lshl_add_u64 v[154:155], v[182:183], 0, s[54:55]
	global_load_dwordx4 v[154:157], v[154:155], off offset:256
	v_mfma_f32_16x16x32_bf16 v[38:41], v[244:247], v[212:215], v[38:41]
	v_mfma_f32_16x16x32_bf16 v[6:9], v[244:247], v[216:219], v[6:9]
	s_waitcnt lgkmcnt(15)
	v_mfma_f32_16x16x32_bf16 v[2:5], v[248:251], v[216:219], v[2:5]
	ds_read_b128 v[244:247], v207 offset:45056
	ds_read_b128 v[216:219], v206 offset:6144
	v_mfma_f32_16x16x32_bf16 v[98:101], v[248:251], v[190:193], v[98:101]
	v_mfma_f32_16x16x32_bf16 v[66:69], v[248:251], v[208:211], v[66:69]
	v_mfma_f32_16x16x32_bf16 v[34:37], v[248:251], v[212:215], v[34:37]
	ds_read_b128 v[248:251], v207 offset:47104
	s_waitcnt lgkmcnt(3)
	s_barrier
;   __device__ __forceinline__ u16* XB() const { return (u16*)(ws + O_XB); }
; DI float bflo(u32 v) { return __uint_as_float(v << 16); }
; DI float bfhi(u32 v) { return __uint_as_float(v & 0xffff0000u); }
; DI f32x4 mfma16(bf16x8 a, bf16x8 b, f32x4 c) { return __builtin_amdgcn_mfma_f32_16x16x32_bf16(a, b, c, 0, 0, 0); }
; #define EPI_LOOP(MT_, NT_)                                                \
;   const int l_ = ltid() & 63, w_ = ltid() >> 6;                           \
;   const int wm_ = w_ >> 1, wn_ = w_ & 1, fr_ = l_ & 15, fq_ = l_ >> 4;    \
;   _Pragma("unroll") for (int mi = 0; mi < MT_; ++mi)                      \
;   _Pragma("unroll") for (int ni = 0; ni < NT_; ++ni)
; template <int MT, int NT>
; DI void gemm_core(const u16* __restrict__ A, int lda, const u16* __restrict__ B, int ldb, int K,
;                   f32x4 (&acc)[MT][NT], char* smem) {
;     ...
;     for (int kk = 0; kk < 2; ++kk) {
;       bf16x8 xf[MT], wf[NT];
; #pragma unroll
;       for (int mi = 0; mi < MT; ++mi)
;         xf[mi] = *(const bf16x8*)(as + (wm * (MT * 16) + mi * 16 + fr) * 128 + (((kk * 4 + fq) ^ fsw) * 16));
; #pragma unroll
;       for (int ni = 0; ni < NT; ++ni)
;         wf[ni] = *(const bf16x8*)(bs + (wn * (NT * 16) + ni * 16 + fr) * 128 + (((kk * 4 + fq) ^ fsw) * 16));
;       __builtin_amdgcn_s_setprio(1);
; #pragma unroll
;       for (int mi = 0; mi < MT; ++mi)
; #pragma unroll
;         for (int ni = 0; ni < NT; ++ni) acc[mi][ni] = mfma16(wf[ni], xf[mi], acc[mi][ni]);
;       __builtin_amdgcn_s_setprio(0);
;     }
;   }
; DI void phase_resgemm(const Params& p, const u16* A, int lda, const u16* W, int ldw, int K, char* smem) {
;     ...
;     EPI_LOOP(4, 8) {
;       const int row = r0 + wm_ * 64 + mi * 16 + fr_, col = c0 + wn_ * 128 + ni * 16 + fq_ * 4;
;       const uint2 xb = *(const uint2*)(p.XB() + (size_t)row * LDX + col);
;       float4 o;
;       o.x = DN_ALPHA * bflo(xb.x) + acc[mi][ni][0]; o.y = DN_ALPHA * bfhi(xb.x) + acc[mi][ni][1];
;       o.z = DN_ALPHA * bflo(xb.y) + acc[mi][ni][2]; o.w = DN_ALPHA * bfhi(xb.y) + acc[mi][ni][3];
;       *(float4*)(p.out + (size_t)row * 1024 + col) = o;
	v_or_b32_e32 v206, s9, v186
	v_add_u32_e32 v207, v206, v188
	v_add_u32_e32 v206, v206, v187
	v_mfma_f32_16x16x32_bf16 v[158:161], v[220:223], v[194:197], v[158:161]
	v_mfma_f32_16x16x32_bf16 v[94:97], v[220:223], v[198:201], v[94:97]
	v_mfma_f32_16x16x32_bf16 v[62:65], v[220:223], v[202:205], v[62:65]
	s_waitcnt lgkmcnt(1)
	v_mfma_f32_16x16x32_bf16 v[30:33], v[220:223], v[216:219], v[30:33]
	ds_read_b128 v[190:193], v206
	v_mfma_f32_16x16x32_bf16 v[150:153], v[224:227], v[194:197], v[150:153]
	ds_read_b128 v[220:223], v207 offset:32768
	v_mfma_f32_16x16x32_bf16 v[90:93], v[224:227], v[198:201], v[90:93]
	v_mfma_f32_16x16x32_bf16 v[58:61], v[224:227], v[202:205], v[58:61]
	v_mfma_f32_16x16x32_bf16 v[26:29], v[224:227], v[216:219], v[26:29]
	ds_read_b128 v[208:211], v206 offset:2048
	v_mfma_f32_16x16x32_bf16 v[146:149], v[228:231], v[194:197], v[146:149]
	ds_read_b128 v[224:227], v207 offset:34816
	v_mfma_f32_16x16x32_bf16 v[86:89], v[228:231], v[198:201], v[86:89]
	v_mfma_f32_16x16x32_bf16 v[54:57], v[228:231], v[202:205], v[54:57]
	v_mfma_f32_16x16x32_bf16 v[22:25], v[228:231], v[216:219], v[22:25]
	ds_read_b128 v[212:215], v206 offset:4096
	v_mfma_f32_16x16x32_bf16 v[126:129], v[232:235], v[194:197], v[126:129]
	ds_read_b128 v[228:231], v207 offset:36864
	v_mfma_f32_16x16x32_bf16 v[82:85], v[232:235], v[198:201], v[82:85]
	v_mfma_f32_16x16x32_bf16 v[50:53], v[232:235], v[202:205], v[50:53]
	v_mfma_f32_16x16x32_bf16 v[18:21], v[232:235], v[216:219], v[18:21]
	v_mfma_f32_16x16x32_bf16 v[110:113], v[236:239], v[194:197], v[110:113]
	ds_read_b128 v[232:235], v207 offset:38912
	v_mfma_f32_16x16x32_bf16 v[78:81], v[236:239], v[198:201], v[78:81]
	v_mfma_f32_16x16x32_bf16 v[46:49], v[236:239], v[202:205], v[46:49]
	v_mfma_f32_16x16x32_bf16 v[14:17], v[236:239], v[216:219], v[14:17]
	v_mfma_f32_16x16x32_bf16 v[106:109], v[240:243], v[194:197], v[106:109]
	ds_read_b128 v[236:239], v207 offset:40960
	v_mfma_f32_16x16x32_bf16 v[74:77], v[240:243], v[198:201], v[74:77]
	v_mfma_f32_16x16x32_bf16 v[42:45], v[240:243], v[202:205], v[42:45]
	v_mfma_f32_16x16x32_bf16 v[10:13], v[240:243], v[216:219], v[10:13]
	v_mfma_f32_16x16x32_bf16 v[102:105], v[244:247], v[194:197], v[102:105]
	ds_read_b128 v[240:243], v207 offset:43008
	v_mfma_f32_16x16x32_bf16 v[70:73], v[244:247], v[198:201], v[70:73]
	v_mfma_f32_16x16x32_bf16 v[38:41], v[244:247], v[202:205], v[38:41]
	v_mfma_f32_16x16x32_bf16 v[6:9], v[244:247], v[216:219], v[6:9]
	s_waitcnt lgkmcnt(9)
	v_mfma_f32_16x16x32_bf16 v[2:5], v[248:251], v[216:219], v[2:5]
	ds_read_b128 v[244:247], v207 offset:45056
	ds_read_b128 v[216:219], v206 offset:6144
	v_mfma_f32_16x16x32_bf16 v[98:101], v[248:251], v[194:197], v[98:101]
	v_mfma_f32_16x16x32_bf16 v[66:69], v[248:251], v[198:201], v[66:69]
	v_mfma_f32_16x16x32_bf16 v[34:37], v[248:251], v[202:205], v[34:37]
	ds_read_b128 v[248:251], v207 offset:47104
	s_cmp_lg_u32 s7, 64
	s_mov_b32 s5, s8
	s_mov_b32 s6, s7
	s_cbranch_scc1 .LBB0_797
	s_waitcnt vmcnt(0) lgkmcnt(0)
	v_mov_b32_e32 v170, 0x358637bd
	v_mov_b32_e32 v194, 0x25a08
	v_mbcnt_lo_u32_b32 v195, -1, 0
	v_mbcnt_hi_u32_b32 v196, -1, v195
	v_mov_b32_e32 v197, 0x24000
	v_mov_b32_e32 v198, 0x1fa0
	v_mov_b32_e32 v199, 0x41b17218
	v_mov_b32_e32 v200, 0x7e800
	v_mov_b32_e32 v201, 0xfd0
	v_mov_b32_e32 v202, 0x100
	v_mov_b32_e32 v203, 0x200
	v_mov_b32_e32 v204, 0x7f61b1e6
	v_mov_b32_e32 v205, 0xff800000
	v_mov_b32_e32 v206, 0x3f80
	v_mov_b32_e32 v207, 0x1d400
	v_mov_b32_e32 v0, v171
	s_waitcnt vmcnt(7)
	v_mov_b32_e32 v115, v171
	s_barrier
	s_waitcnt vmcnt(5)
	v_mov_b64_e32 v[118:119], s[60:61]
	v_ashrrev_i32_e32 v114, 1, v115
	v_and_b32_e32 v114, 0xffffffc0, v114
	v_add_u32_e32 v114, s1, v114
	v_and_or_b32 v114, v0, 15, v114
	v_lshlrev_b32_e32 v115, 1, v115
	v_lshrrev_b32_e32 v0, 2, v0
	v_and_b32_e32 v115, 0x80, v115
	v_and_b32_e32 v0, 12, v0
	v_or3_b32 v115, v0, v115, s0
	v_mad_i64_i32 v[116:117], s[0:1], v114, s59, v[118:119]
	v_lshlrev_b32_e32 v0, 1, v115
	v_lshl_add_u64 v[124:125], v[116:117], 0, v[0:1]
	global_load_dwordx2 v[120:121], v[124:125], off
	v_lshlrev_b32_e32 v116, 2, v115
	v_ashrrev_i32_e32 v115, 31, v114
	v_lshlrev_b64 v[122:123], 12, v[114:115]
	v_mov_b32_e32 v117, v1
	v_lshl_add_u64 v[122:123], s[86:87], 0, v[122:123]
	s_waitcnt vmcnt(4)
	v_lshl_add_u64 v[130:131], v[122:123], 0, v[116:117]
	s_add_i32 s4, s4, 1
	s_waitcnt vmcnt(0)
	v_lshlrev_b32_e32 v122, 16, v120
	v_and_b32_e32 v123, 0xffff0000, v120
	v_lshlrev_b32_e32 v132, 16, v121
	v_and_b32_e32 v133, 0xffff0000, v121
	v_pk_fma_f32 v[120:121], v[122:123], s[74:75], v[158:159] op_sel_hi:[1,0,1]
	v_pk_fma_f32 v[122:123], v[132:133], s[74:75], v[160:161] op_sel_hi:[1,0,1]
	global_store_dwordx4 v[130:131], v[120:123], off
	global_load_dwordx2 v[120:121], v[124:125], off offset:32
	s_waitcnt vmcnt(0)
	v_lshlrev_b32_e32 v132, 16, v121
	v_lshlrev_b32_e32 v122, 16, v120
	v_and_b32_e32 v123, 0xffff0000, v120
	v_and_b32_e32 v133, 0xffff0000, v121
	v_pk_fma_f32 v[120:121], v[122:123], s[74:75], v[150:151] op_sel_hi:[1,0,1]
	v_pk_fma_f32 v[122:123], v[132:133], s[74:75], v[152:153] op_sel_hi:[1,0,1]
	global_store_dwordx4 v[130:131], v[120:123], off offset:64
	global_load_dwordx2 v[120:121], v[124:125], off offset:64
	s_waitcnt vmcnt(0)
	v_lshlrev_b32_e32 v132, 16, v121
	v_lshlrev_b32_e32 v122, 16, v120
	v_and_b32_e32 v123, 0xffff0000, v120
	v_and_b32_e32 v133, 0xffff0000, v121
	v_pk_fma_f32 v[120:121], v[122:123], s[74:75], v[146:147] op_sel_hi:[1,0,1]
	v_pk_fma_f32 v[122:123], v[132:133], s[74:75], v[148:149] op_sel_hi:[1,0,1]
	global_store_dwordx4 v[130:131], v[120:123], off offset:128
	global_load_dwordx2 v[120:121], v[124:125], off offset:96
	s_waitcnt vmcnt(0)
;   __device__ __forceinline__ u16* XB() const { return (u16*)(ws + O_XB); }
; DI float bflo(u32 v) { return __uint_as_float(v << 16); }
; DI float bfhi(u32 v) { return __uint_as_float(v & 0xffff0000u); }
; #define EPI_LOOP(MT_, NT_)                                                \
;   const int l_ = ltid() & 63, w_ = ltid() >> 6;                           \
;   const int wm_ = w_ >> 1, wn_ = w_ & 1, fr_ = l_ & 15, fq_ = l_ >> 4;    \
;   _Pragma("unroll") for (int mi = 0; mi < MT_; ++mi)                      \
;   _Pragma("unroll") for (int ni = 0; ni < NT_; ++ni)
; DI void phase_resgemm(const Params& p, const u16* A, int lda, const u16* W, int ldw, int K, char* smem) {
;     ...
;     EPI_LOOP(4, 8) {
;       const int row = r0 + wm_ * 64 + mi * 16 + fr_, col = c0 + wn_ * 128 + ni * 16 + fq_ * 4;
;       const uint2 xb = *(const uint2*)(p.XB() + (size_t)row * LDX + col);
;       float4 o;
;       o.x = DN_ALPHA * bflo(xb.x) + acc[mi][ni][0]; o.y = DN_ALPHA * bfhi(xb.x) + acc[mi][ni][1];
;       o.z = DN_ALPHA * bflo(xb.y) + acc[mi][ni][2]; o.w = DN_ALPHA * bfhi(xb.y) + acc[mi][ni][3];
;       *(float4*)(p.out + (size_t)row * 1024 + col) = o;
	v_lshlrev_b32_e32 v132, 16, v121
	v_lshlrev_b32_e32 v122, 16, v120
	v_and_b32_e32 v123, 0xffff0000, v120
	v_and_b32_e32 v133, 0xffff0000, v121
	v_pk_fma_f32 v[120:121], v[122:123], s[74:75], v[126:127] op_sel_hi:[1,0,1]
	v_pk_fma_f32 v[122:123], v[132:133], s[74:75], v[128:129] op_sel_hi:[1,0,1]
	global_store_dwordx4 v[130:131], v[120:123], off offset:192
	global_load_dwordx2 v[120:121], v[124:125], off offset:128
	s_waitcnt vmcnt(0)
	v_lshlrev_b32_e32 v122, 16, v120
	v_and_b32_e32 v123, 0xffff0000, v120
	v_lshlrev_b32_e32 v120, 16, v121
	v_and_b32_e32 v121, 0xffff0000, v121
	v_pk_fma_f32 v[110:111], v[122:123], s[74:75], v[110:111] op_sel_hi:[1,0,1]
	v_pk_fma_f32 v[112:113], v[120:121], s[74:75], v[112:113] op_sel_hi:[1,0,1]
	global_store_dwordx4 v[130:131], v[110:113], off offset:256
	global_load_dwordx2 v[110:111], v[124:125], off offset:160
	s_waitcnt vmcnt(0)
	v_lshlrev_b32_e32 v112, 16, v110
	v_and_b32_e32 v113, 0xffff0000, v110
	v_lshlrev_b32_e32 v110, 16, v111
	v_and_b32_e32 v111, 0xffff0000, v111
	v_pk_fma_f32 v[106:107], v[112:113], s[74:75], v[106:107] op_sel_hi:[1,0,1]
	v_pk_fma_f32 v[108:109], v[110:111], s[74:75], v[108:109] op_sel_hi:[1,0,1]
	global_store_dwordx4 v[130:131], v[106:109], off offset:320
	global_load_dwordx2 v[106:107], v[124:125], off offset:192
	s_waitcnt vmcnt(0)
	v_lshlrev_b32_e32 v108, 16, v106
	v_and_b32_e32 v109, 0xffff0000, v106
	v_lshlrev_b32_e32 v106, 16, v107
	v_and_b32_e32 v107, 0xffff0000, v107
	v_pk_fma_f32 v[102:103], v[108:109], s[74:75], v[102:103] op_sel_hi:[1,0,1]
	v_pk_fma_f32 v[104:105], v[106:107], s[74:75], v[104:105] op_sel_hi:[1,0,1]
	global_store_dwordx4 v[130:131], v[102:105], off offset:384
	global_load_dwordx2 v[102:103], v[124:125], off offset:224
	s_waitcnt vmcnt(0)
	v_lshlrev_b32_e32 v108, 16, v102
	v_or_b32_e32 v104, 16, v114
	v_and_b32_e32 v109, 0xffff0000, v102
	v_lshlrev_b32_e32 v102, 16, v103
	v_and_b32_e32 v103, 0xffff0000, v103
	v_mad_i64_i32 v[106:107], s[0:1], v104, s59, v[118:119]
	v_pk_fma_f32 v[98:99], v[108:109], s[74:75], v[98:99] op_sel_hi:[1,0,1]
	v_pk_fma_f32 v[100:101], v[102:103], s[74:75], v[100:101] op_sel_hi:[1,0,1]
	v_lshl_add_u64 v[106:107], v[106:107], 0, v[0:1]
	global_store_dwordx4 v[130:131], v[98:101], off offset:448
	global_load_dwordx2 v[98:99], v[106:107], off
	v_ashrrev_i32_e32 v105, 31, v104
	v_lshlrev_b64 v[100:101], 12, v[104:105]
	v_lshl_add_u64 v[100:101], s[86:87], 0, v[100:101]
	v_lshl_add_u64 v[100:101], v[100:101], 0, v[116:117]
	s_waitcnt vmcnt(0)
	v_lshlrev_b32_e32 v102, 16, v98
	v_and_b32_e32 v103, 0xffff0000, v98
	v_lshlrev_b32_e32 v98, 16, v99
	v_and_b32_e32 v99, 0xffff0000, v99
	v_pk_fma_f32 v[94:95], v[102:103], s[74:75], v[94:95] op_sel_hi:[1,0,1]
	v_pk_fma_f32 v[96:97], v[98:99], s[74:75], v[96:97] op_sel_hi:[1,0,1]
	global_store_dwordx4 v[100:101], v[94:97], off
	global_load_dwordx2 v[94:95], v[106:107], off offset:32
	s_waitcnt vmcnt(0)
	v_lshlrev_b32_e32 v96, 16, v94
	v_and_b32_e32 v97, 0xffff0000, v94
	v_lshlrev_b32_e32 v94, 16, v95
	v_and_b32_e32 v95, 0xffff0000, v95
	v_pk_fma_f32 v[90:91], v[96:97], s[74:75], v[90:91] op_sel_hi:[1,0,1]
	v_pk_fma_f32 v[92:93], v[94:95], s[74:75], v[92:93] op_sel_hi:[1,0,1]
	global_store_dwordx4 v[100:101], v[90:93], off offset:64
	global_load_dwordx2 v[90:91], v[106:107], off offset:64
	s_waitcnt vmcnt(0)
	v_lshlrev_b32_e32 v92, 16, v90
	v_and_b32_e32 v93, 0xffff0000, v90
	v_lshlrev_b32_e32 v90, 16, v91
	v_and_b32_e32 v91, 0xffff0000, v91
	v_pk_fma_f32 v[86:87], v[92:93], s[74:75], v[86:87] op_sel_hi:[1,0,1]
	v_pk_fma_f32 v[88:89], v[90:91], s[74:75], v[88:89] op_sel_hi:[1,0,1]
	global_store_dwordx4 v[100:101], v[86:89], off offset:128
	global_load_dwordx2 v[86:87], v[106:107], off offset:96
	s_waitcnt vmcnt(0)
	v_lshlrev_b32_e32 v88, 16, v86
	v_and_b32_e32 v89, 0xffff0000, v86
	v_lshlrev_b32_e32 v86, 16, v87
	v_and_b32_e32 v87, 0xffff0000, v87
	v_pk_fma_f32 v[82:83], v[88:89], s[74:75], v[82:83] op_sel_hi:[1,0,1]
	v_pk_fma_f32 v[84:85], v[86:87], s[74:75], v[84:85] op_sel_hi:[1,0,1]
	global_store_dwordx4 v[100:101], v[82:85], off offset:192
	global_load_dwordx2 v[82:83], v[106:107], off offset:128
	s_waitcnt vmcnt(0)
	v_lshlrev_b32_e32 v84, 16, v82
	v_and_b32_e32 v85, 0xffff0000, v82
	v_lshlrev_b32_e32 v82, 16, v83
	v_and_b32_e32 v83, 0xffff0000, v83
	v_pk_fma_f32 v[78:79], v[84:85], s[74:75], v[78:79] op_sel_hi:[1,0,1]
	v_pk_fma_f32 v[80:81], v[82:83], s[74:75], v[80:81] op_sel_hi:[1,0,1]
	global_store_dwordx4 v[100:101], v[78:81], off offset:256
	global_load_dwordx2 v[78:79], v[106:107], off offset:160
	s_waitcnt vmcnt(0)
	v_lshlrev_b32_e32 v80, 16, v78
	v_and_b32_e32 v81, 0xffff0000, v78
	v_lshlrev_b32_e32 v78, 16, v79
	v_and_b32_e32 v79, 0xffff0000, v79
	v_pk_fma_f32 v[74:75], v[80:81], s[74:75], v[74:75] op_sel_hi:[1,0,1]
	v_pk_fma_f32 v[76:77], v[78:79], s[74:75], v[76:77] op_sel_hi:[1,0,1]
	global_store_dwordx4 v[100:101], v[74:77], off offset:320
	global_load_dwordx2 v[74:75], v[106:107], off offset:192
	s_waitcnt vmcnt(0)
	v_lshlrev_b32_e32 v76, 16, v74
	v_and_b32_e32 v77, 0xffff0000, v74
	v_lshlrev_b32_e32 v74, 16, v75
	v_and_b32_e32 v75, 0xffff0000, v75
	v_pk_fma_f32 v[70:71], v[76:77], s[74:75], v[70:71] op_sel_hi:[1,0,1]
	v_pk_fma_f32 v[72:73], v[74:75], s[74:75], v[72:73] op_sel_hi:[1,0,1]
	global_store_dwordx4 v[100:101], v[70:73], off offset:384
	global_load_dwordx2 v[70:71], v[106:107], off offset:224
	s_waitcnt vmcnt(0)
;   __device__ __forceinline__ u16* XB() const { return (u16*)(ws + O_XB); }
; DI float bflo(u32 v) { return __uint_as_float(v << 16); }
; DI float bfhi(u32 v) { return __uint_as_float(v & 0xffff0000u); }
; #define EPI_LOOP(MT_, NT_)                                                \
;   const int l_ = ltid() & 63, w_ = ltid() >> 6;                           \
;   const int wm_ = w_ >> 1, wn_ = w_ & 1, fr_ = l_ & 15, fq_ = l_ >> 4;    \
;   _Pragma("unroll") for (int mi = 0; mi < MT_; ++mi)                      \
;   _Pragma("unroll") for (int ni = 0; ni < NT_; ++ni)
; DI void phase_resgemm(const Params& p, const u16* A, int lda, const u16* W, int ldw, int K, char* smem) {
;     ...
;     EPI_LOOP(4, 8) {
;       const int row = r0 + wm_ * 64 + mi * 16 + fr_, col = c0 + wn_ * 128 + ni * 16 + fq_ * 4;
;       const uint2 xb = *(const uint2*)(p.XB() + (size_t)row * LDX + col);
;       float4 o;
;       o.x = DN_ALPHA * bflo(xb.x) + acc[mi][ni][0]; o.y = DN_ALPHA * bfhi(xb.x) + acc[mi][ni][1];
;       o.z = DN_ALPHA * bflo(xb.y) + acc[mi][ni][2]; o.w = DN_ALPHA * bfhi(xb.y) + acc[mi][ni][3];
;       *(float4*)(p.out + (size_t)row * 1024 + col) = o;
	v_lshlrev_b32_e32 v76, 16, v70
	v_or_b32_e32 v72, 32, v114
	v_and_b32_e32 v77, 0xffff0000, v70
	v_lshlrev_b32_e32 v70, 16, v71
	v_and_b32_e32 v71, 0xffff0000, v71
	v_mad_i64_i32 v[74:75], s[0:1], v72, s59, v[118:119]
	v_pk_fma_f32 v[66:67], v[76:77], s[74:75], v[66:67] op_sel_hi:[1,0,1]
	v_pk_fma_f32 v[68:69], v[70:71], s[74:75], v[68:69] op_sel_hi:[1,0,1]
	v_lshl_add_u64 v[74:75], v[74:75], 0, v[0:1]
	global_store_dwordx4 v[100:101], v[66:69], off offset:448
	global_load_dwordx2 v[66:67], v[74:75], off
	v_ashrrev_i32_e32 v73, 31, v72
	v_lshlrev_b64 v[68:69], 12, v[72:73]
	v_lshl_add_u64 v[68:69], s[86:87], 0, v[68:69]
	v_lshl_add_u64 v[68:69], v[68:69], 0, v[116:117]
	s_waitcnt vmcnt(0)
	v_lshlrev_b32_e32 v70, 16, v66
	v_and_b32_e32 v71, 0xffff0000, v66
	v_lshlrev_b32_e32 v66, 16, v67
	v_and_b32_e32 v67, 0xffff0000, v67
	v_pk_fma_f32 v[62:63], v[70:71], s[74:75], v[62:63] op_sel_hi:[1,0,1]
	v_pk_fma_f32 v[64:65], v[66:67], s[74:75], v[64:65] op_sel_hi:[1,0,1]
	global_store_dwordx4 v[68:69], v[62:65], off
	global_load_dwordx2 v[62:63], v[74:75], off offset:32
	s_waitcnt vmcnt(0)
	v_lshlrev_b32_e32 v64, 16, v62
	v_and_b32_e32 v65, 0xffff0000, v62
	v_lshlrev_b32_e32 v62, 16, v63
	v_and_b32_e32 v63, 0xffff0000, v63
	v_pk_fma_f32 v[58:59], v[64:65], s[74:75], v[58:59] op_sel_hi:[1,0,1]
	v_pk_fma_f32 v[60:61], v[62:63], s[74:75], v[60:61] op_sel_hi:[1,0,1]
	global_store_dwordx4 v[68:69], v[58:61], off offset:64
	global_load_dwordx2 v[58:59], v[74:75], off offset:64
	s_waitcnt vmcnt(0)
	v_lshlrev_b32_e32 v60, 16, v58
	v_and_b32_e32 v61, 0xffff0000, v58
	v_lshlrev_b32_e32 v58, 16, v59
	v_and_b32_e32 v59, 0xffff0000, v59
	v_pk_fma_f32 v[54:55], v[60:61], s[74:75], v[54:55] op_sel_hi:[1,0,1]
	v_pk_fma_f32 v[56:57], v[58:59], s[74:75], v[56:57] op_sel_hi:[1,0,1]
	global_store_dwordx4 v[68:69], v[54:57], off offset:128
	global_load_dwordx2 v[54:55], v[74:75], off offset:96
	s_waitcnt vmcnt(0)
	v_lshlrev_b32_e32 v56, 16, v54
	v_and_b32_e32 v57, 0xffff0000, v54
	v_lshlrev_b32_e32 v54, 16, v55
	v_and_b32_e32 v55, 0xffff0000, v55
	v_pk_fma_f32 v[50:51], v[56:57], s[74:75], v[50:51] op_sel_hi:[1,0,1]
	v_pk_fma_f32 v[52:53], v[54:55], s[74:75], v[52:53] op_sel_hi:[1,0,1]
	global_store_dwordx4 v[68:69], v[50:53], off offset:192
	global_load_dwordx2 v[50:51], v[74:75], off offset:128
	s_waitcnt vmcnt(0)
	v_lshlrev_b32_e32 v52, 16, v50
	v_and_b32_e32 v53, 0xffff0000, v50
	v_lshlrev_b32_e32 v50, 16, v51
	v_and_b32_e32 v51, 0xffff0000, v51
	v_pk_fma_f32 v[46:47], v[52:53], s[74:75], v[46:47] op_sel_hi:[1,0,1]
	v_pk_fma_f32 v[48:49], v[50:51], s[74:75], v[48:49] op_sel_hi:[1,0,1]
	global_store_dwordx4 v[68:69], v[46:49], off offset:256
	global_load_dwordx2 v[46:47], v[74:75], off offset:160
	s_waitcnt vmcnt(0)
	v_lshlrev_b32_e32 v48, 16, v46
	v_and_b32_e32 v49, 0xffff0000, v46
	v_lshlrev_b32_e32 v46, 16, v47
	v_and_b32_e32 v47, 0xffff0000, v47
	v_pk_fma_f32 v[42:43], v[48:49], s[74:75], v[42:43] op_sel_hi:[1,0,1]
	v_pk_fma_f32 v[44:45], v[46:47], s[74:75], v[44:45] op_sel_hi:[1,0,1]
	global_store_dwordx4 v[68:69], v[42:45], off offset:320
	global_load_dwordx2 v[42:43], v[74:75], off offset:192
	s_waitcnt vmcnt(0)
	v_lshlrev_b32_e32 v44, 16, v42
	v_and_b32_e32 v45, 0xffff0000, v42
	v_lshlrev_b32_e32 v42, 16, v43
	v_and_b32_e32 v43, 0xffff0000, v43
	v_pk_fma_f32 v[38:39], v[44:45], s[74:75], v[38:39] op_sel_hi:[1,0,1]
	v_pk_fma_f32 v[40:41], v[42:43], s[74:75], v[40:41] op_sel_hi:[1,0,1]
	global_store_dwordx4 v[68:69], v[38:41], off offset:384
	global_load_dwordx2 v[38:39], v[74:75], off offset:224
	s_waitcnt vmcnt(0)
;   __device__ __forceinline__ u16* XB() const { return (u16*)(ws + O_XB); }
; DI float bflo(u32 v) { return __uint_as_float(v << 16); }
; DI float bfhi(u32 v) { return __uint_as_float(v & 0xffff0000u); }
; #define EPI_LOOP(MT_, NT_)                                                \
;   const int l_ = ltid() & 63, w_ = ltid() >> 6;                           \
;   const int wm_ = w_ >> 1, wn_ = w_ & 1, fr_ = l_ & 15, fq_ = l_ >> 4;    \
;   _Pragma("unroll") for (int mi = 0; mi < MT_; ++mi)                      \
;   _Pragma("unroll") for (int ni = 0; ni < NT_; ++ni)
; DI void phase_resgemm(const Params& p, const u16* A, int lda, const u16* W, int ldw, int K, char* smem) {
;     ...
;     EPI_LOOP(4, 8) {
;       const int row = r0 + wm_ * 64 + mi * 16 + fr_, col = c0 + wn_ * 128 + ni * 16 + fq_ * 4;
;       const uint2 xb = *(const uint2*)(p.XB() + (size_t)row * LDX + col);
;       float4 o;
;       o.x = DN_ALPHA * bflo(xb.x) + acc[mi][ni][0]; o.y = DN_ALPHA * bfhi(xb.x) + acc[mi][ni][1];
;       o.z = DN_ALPHA * bflo(xb.y) + acc[mi][ni][2]; o.w = DN_ALPHA * bfhi(xb.y) + acc[mi][ni][3];
;       *(float4*)(p.out + (size_t)row * 1024 + col) = o;
	v_lshlrev_b32_e32 v44, 16, v38
	v_or_b32_e32 v40, 48, v114
	v_and_b32_e32 v45, 0xffff0000, v38
	v_lshlrev_b32_e32 v38, 16, v39
	v_and_b32_e32 v39, 0xffff0000, v39
	v_mad_i64_i32 v[42:43], s[0:1], v40, s59, v[118:119]
	v_pk_fma_f32 v[34:35], v[44:45], s[74:75], v[34:35] op_sel_hi:[1,0,1]
	v_pk_fma_f32 v[36:37], v[38:39], s[74:75], v[36:37] op_sel_hi:[1,0,1]
	v_lshl_add_u64 v[42:43], v[42:43], 0, v[0:1]
	global_store_dwordx4 v[68:69], v[34:37], off offset:448
	global_load_dwordx2 v[34:35], v[42:43], off
	v_ashrrev_i32_e32 v41, 31, v40
	v_lshlrev_b64 v[36:37], 12, v[40:41]
	v_lshl_add_u64 v[36:37], s[86:87], 0, v[36:37]
	v_lshl_add_u64 v[36:37], v[36:37], 0, v[116:117]
	s_mov_b64 s[0:1], 0
	s_waitcnt vmcnt(0)
	v_lshlrev_b32_e32 v38, 16, v34
	v_and_b32_e32 v39, 0xffff0000, v34
	v_lshlrev_b32_e32 v34, 16, v35
	v_and_b32_e32 v35, 0xffff0000, v35
	v_pk_fma_f32 v[30:31], v[38:39], s[74:75], v[30:31] op_sel_hi:[1,0,1]
	v_pk_fma_f32 v[32:33], v[34:35], s[74:75], v[32:33] op_sel_hi:[1,0,1]
	global_store_dwordx4 v[36:37], v[30:33], off
	global_load_dwordx2 v[30:31], v[42:43], off offset:32
	s_waitcnt vmcnt(0)
	v_lshlrev_b32_e32 v32, 16, v30
	v_and_b32_e32 v33, 0xffff0000, v30
	v_lshlrev_b32_e32 v30, 16, v31
	v_and_b32_e32 v31, 0xffff0000, v31
	v_pk_fma_f32 v[26:27], v[32:33], s[74:75], v[26:27] op_sel_hi:[1,0,1]
	v_pk_fma_f32 v[28:29], v[30:31], s[74:75], v[28:29] op_sel_hi:[1,0,1]
	global_store_dwordx4 v[36:37], v[26:29], off offset:64
	global_load_dwordx2 v[26:27], v[42:43], off offset:64
	s_waitcnt vmcnt(0)
	v_lshlrev_b32_e32 v28, 16, v26
	v_and_b32_e32 v29, 0xffff0000, v26
	v_lshlrev_b32_e32 v26, 16, v27
	v_and_b32_e32 v27, 0xffff0000, v27
	v_pk_fma_f32 v[22:23], v[28:29], s[74:75], v[22:23] op_sel_hi:[1,0,1]
	v_pk_fma_f32 v[24:25], v[26:27], s[74:75], v[24:25] op_sel_hi:[1,0,1]
	global_store_dwordx4 v[36:37], v[22:25], off offset:128
	global_load_dwordx2 v[22:23], v[42:43], off offset:96
	s_waitcnt vmcnt(0)
	v_lshlrev_b32_e32 v24, 16, v22
	v_and_b32_e32 v25, 0xffff0000, v22
	v_lshlrev_b32_e32 v22, 16, v23
	v_and_b32_e32 v23, 0xffff0000, v23
	v_pk_fma_f32 v[18:19], v[24:25], s[74:75], v[18:19] op_sel_hi:[1,0,1]
	v_pk_fma_f32 v[20:21], v[22:23], s[74:75], v[20:21] op_sel_hi:[1,0,1]
	global_store_dwordx4 v[36:37], v[18:21], off offset:192
	global_load_dwordx2 v[18:19], v[42:43], off offset:128
	s_waitcnt vmcnt(0)
	v_lshlrev_b32_e32 v20, 16, v18
	v_and_b32_e32 v21, 0xffff0000, v18
	v_lshlrev_b32_e32 v18, 16, v19
	v_and_b32_e32 v19, 0xffff0000, v19
	v_pk_fma_f32 v[14:15], v[20:21], s[74:75], v[14:15] op_sel_hi:[1,0,1]
	v_pk_fma_f32 v[16:17], v[18:19], s[74:75], v[16:17] op_sel_hi:[1,0,1]
	global_store_dwordx4 v[36:37], v[14:17], off offset:256
	global_load_dwordx2 v[14:15], v[42:43], off offset:160
	s_waitcnt vmcnt(0)
	v_lshlrev_b32_e32 v16, 16, v14
	v_and_b32_e32 v17, 0xffff0000, v14
	v_lshlrev_b32_e32 v14, 16, v15
	v_and_b32_e32 v15, 0xffff0000, v15
	v_pk_fma_f32 v[10:11], v[16:17], s[74:75], v[10:11] op_sel_hi:[1,0,1]
	v_pk_fma_f32 v[12:13], v[14:15], s[74:75], v[12:13] op_sel_hi:[1,0,1]
	global_store_dwordx4 v[36:37], v[10:13], off offset:320
	global_load_dwordx2 v[10:11], v[42:43], off offset:192
	s_waitcnt vmcnt(0)
	v_lshlrev_b32_e32 v12, 16, v10
	v_and_b32_e32 v13, 0xffff0000, v10
	v_lshlrev_b32_e32 v10, 16, v11
	v_and_b32_e32 v11, 0xffff0000, v11
	v_pk_fma_f32 v[6:7], v[12:13], s[74:75], v[6:7] op_sel_hi:[1,0,1]
	v_pk_fma_f32 v[8:9], v[10:11], s[74:75], v[8:9] op_sel_hi:[1,0,1]
	global_store_dwordx4 v[36:37], v[6:9], off offset:384
	global_load_dwordx2 v[6:7], v[42:43], off offset:224
	s_waitcnt vmcnt(0)
	v_lshlrev_b32_e32 v8, 16, v6
	v_and_b32_e32 v9, 0xffff0000, v6
	v_lshlrev_b32_e32 v6, 16, v7
	v_and_b32_e32 v7, 0xffff0000, v7
	v_pk_fma_f32 v[2:3], v[8:9], s[74:75], v[2:3] op_sel_hi:[1,0,1]
	v_pk_fma_f32 v[4:5], v[6:7], s[74:75], v[4:5] op_sel_hi:[1,0,1]
	global_store_dwordx4 v[36:37], v[2:5], off offset:448
	s_branch .LBB0_794
